# scan0 loops: ds_read2_b64 split as well (no gain expected from quick timing)
# speedup vs baseline: 1.0328x; 1.0156x over previous
.LBB0_854:
	s_or_b64 exec, exec, s[96:97]
	s_min_i32 s16, s77, s3
	s_lshl_b32 s16, s16, 5
	v_or_b32_e32 v0, s16, v191
	v_xad_u32 v1, v0, -1, s74
	v_cndmask_b32_e64 v0, v1, v0, s[4:5]
	v_add_u32_e32 v1, s16, v192
	v_xad_u32 v3, v1, -1, s74
	v_add_u32_e32 v0, s73, v0
	v_cndmask_b32_e64 v3, v3, v1, s[4:5]
	v_ashrrev_i32_e32 v1, 31, v0
	ds_write_b128 v197, v[4:7] offset:61952
	v_mad_i64_i32 v[4:5], s[16:17], v0, s89, v[180:181]
	v_lshlrev_b64 v[0:1], 11, v[0:1]
	v_lshl_add_u64 v[0:1], v[182:183], 0, v[0:1]
	global_load_dwordx4 v[12:15], v[4:5], off
	global_load_dwordx4 v[20:23], v[0:1], off
	v_add_u32_e32 v0, s73, v3
	v_mad_i64_i32 v[0:1], s[16:17], v0, s89, v[184:185]
	global_load_dwordx4 v[4:7], v[0:1], off
	v_add_u32_e32 v0, 0x8800, v205
	s_waitcnt lgkmcnt(0)
	s_barrier
	ds_read_b64_tr_b16 v[92:93], v204
	ds_read_b64_tr_b16 v[94:95], v204 offset:4352
	ds_read_b64 v[88:89], v0 offset:1024
	ds_read_b64 v[90:91], v0 offset:1056
	ds_read_b64 v[80:81], v0 offset:1088
	ds_read_b64 v[82:83], v0 offset:1120
	ds_read_b64 v[72:73], v0 offset:1152
	ds_read_b64 v[74:75], v0 offset:1184
	ds_read_b64 v[60:61], v0 offset:1216
	ds_read_b64 v[62:63], v0 offset:1248
	v_add_u32_e32 v0, 0x9800, v205
	v_add_u32_e32 v1, 0xb800, v201
	ds_read_b64 v[84:85], v0 offset:1280
	ds_read_b64 v[86:87], v0 offset:1312
	ds_read_b64 v[76:77], v0 offset:1344
	ds_read_b64 v[78:79], v0 offset:1376
	ds_read_b64 v[68:69], v0 offset:1408
	ds_read_b64 v[70:71], v0 offset:1440
	ds_read_b64 v[64:65], v0 offset:1472
	ds_read_b64 v[66:67], v0 offset:1504
	ds_read_b64 v[100:101], v1 offset:1792
	ds_read_b64 v[102:103], v1 offset:1824
	v_add_u32_e32 v0, 0xa800, v201
	ds_read_b64 v[96:97], v0 offset:1536
	ds_read_b64 v[98:99], v0 offset:1568
	ds_read_b64 v[108:109], v0 offset:1600
	ds_read_b64 v[110:111], v0 offset:1632
	ds_read_b64 v[112:113], v1 offset:1856
	ds_read_b64 v[114:115], v1 offset:1888
	s_waitcnt lgkmcnt(6)
	v_mfma_f32_16x16x32_bf16 v[100:103], v[100:103], v[84:87], 0
	s_add_i32 s77, s77, 2
	v_subrev_u32_e32 v222, 64, v222
	s_cmp_ge_u32 s78, s35
	s_waitcnt lgkmcnt(4)
	v_mfma_f32_16x16x32_bf16 v[104:107], v[96:99], v[88:91], 0
	s_waitcnt lgkmcnt(0)
	v_mfma_f32_16x16x32_bf16 v[100:103], v[112:115], v[76:79], v[100:103]
	ds_read_b64 v[112:113], v0 offset:1664
	ds_read_b64 v[114:115], v0 offset:1696
	ds_read_b64 v[116:117], v1 offset:1920
	ds_read_b64 v[118:119], v1 offset:1952
	v_mfma_f32_16x16x32_bf16 v[104:107], v[108:111], v[80:83], v[104:107]
	s_waitcnt lgkmcnt(0)
	v_mfma_f32_16x16x32_bf16 v[100:103], v[116:119], v[68:71], v[100:103]
	ds_read_b64 v[116:117], v0 offset:1728
	ds_read_b64 v[118:119], v0 offset:1760
	ds_read_b64 v[226:227], v1 offset:1984
	ds_read_b64 v[228:229], v1 offset:2016
	v_mov_b32_e32 v0, s93
	v_mfma_f32_16x16x32_bf16 v[96:99], v[96:99], v[84:87], 0
	v_mfma_f32_16x16x32_bf16 v[104:107], v[112:115], v[72:75], v[104:107]
	v_mfma_f32_16x16x32_bf16 v[96:99], v[108:111], v[76:79], v[96:99]
	s_waitcnt lgkmcnt(2)
	v_mfma_f32_16x16x32_bf16 v[104:107], v[116:119], v[60:63], v[104:107]
	s_waitcnt lgkmcnt(0)
	v_mfma_f32_16x16x32_bf16 v[100:103], v[226:229], v[64:67], v[100:103]
	v_mov_b32_e32 v226, s93
	s_nop 4
	v_cndmask_b32_e64 v0, v104, v0, s[8:9]
	v_cndmask_b32_e64 v0, v0, v104, s[10:11]
	v_mfma_f32_16x16x32_bf16 v[96:99], v[112:115], v[68:71], v[96:99]
	v_cndmask_b32_e64 v3, v106, 0, s[12:13]
	v_cndmask_b32_e64 v1, v100, v226, s[8:9]
	v_cndmask_b32_e64 v100, v1, v100, s[10:11]
	v_cndmask_b32_e64 v1, 0, v105, s[10:11]
	v_cndmask_b32_e64 v104, v107, 0, s[14:15]
	v_cvt_pk_bf16_f32 v0, v0, v1
	v_cvt_pk_bf16_f32 v1, v3, v104
	ds_read_b128 v[104:107], v206
	ds_read_b128 v[108:111], v207
	v_mfma_f32_16x16x32_bf16 v[96:99], v[116:119], v[64:67], v[96:99]
	v_cndmask_b32_e64 v101, 0, v101, s[10:11]
	v_cndmask_b32_e64 v102, v102, 0, s[12:13]
	v_cndmask_b32_e64 v103, v103, 0, s[14:15]
	v_mov_b32_e32 v3, v2
	s_waitcnt lgkmcnt(0)
	v_pk_mul_f32 v[110:111], v[54:55], v[110:111]
	s_nop 1
	v_cvt_pk_bf16_f32 v96, v96, v97
	v_cvt_pk_bf16_f32 v97, v98, v99
	v_cvt_pk_bf16_f32 v98, v100, v101
	v_cvt_pk_bf16_f32 v99, v102, v103
	v_mfma_f32_16x16x32_bf16 v[100:103], v[92:95], v[0:3], 0
	v_mul_f32_e64 v0, v58, v106
	v_mul_f32_e64 v1, v59, v107
	v_pk_mul_f32 v[106:107], v[52:53], v[108:109]
	v_pk_mul_f32 v[104:105], v[56:57], v[104:105]
	v_cvt_pk_bf16_f32 v106, v106, v107
	v_cvt_pk_bf16_f32 v107, v110, v111
	ds_read_b128 v[108:111], v208
	ds_read_b128 v[112:115], v209
	v_cvt_pk_bf16_f32 v104, v104, v105
	v_cvt_pk_bf16_f32 v105, v0, v1
	v_mfma_f32_16x16x32_bf16 v[96:99], v[92:95], v[96:99], 0
	s_waitcnt lgkmcnt(1)
	v_pk_mul_f32 v[0:1], v[50:51], v[110:111]
	v_pk_mul_f32 v[108:109], v[48:49], v[108:109]
	s_waitcnt lgkmcnt(0)
	v_pk_mul_f32 v[110:111], v[46:47], v[114:115]
	v_pk_mul_f32 v[112:113], v[44:45], v[112:113]
	v_cvt_pk_bf16_f32 v116, v108, v109
	v_cvt_pk_bf16_f32 v118, v112, v113
	v_cvt_pk_bf16_f32 v119, v110, v111
	ds_read_b128 v[108:111], v210
	ds_read_b128 v[112:115], v211
	v_cvt_pk_bf16_f32 v117, v0, v1
	v_mfma_f32_16x16x32_bf16 v[88:91], v[104:107], v[88:91], v[100:103]
	v_xor_b32_e32 v3, 0xffffffdf, v190
	s_waitcnt lgkmcnt(1)
	v_pk_mul_f32 v[0:1], v[42:43], v[110:111]
	s_waitcnt lgkmcnt(0)
	v_pk_mul_f32 v[114:115], v[38:39], v[114:115]
	v_pk_mul_f32 v[110:111], v[36:37], v[112:113]
	v_pk_mul_f32 v[108:109], v[40:41], v[108:109]
	v_cvt_pk_bf16_f32 v110, v110, v111
	v_cvt_pk_bf16_f32 v111, v114, v115
	ds_read_b128 v[112:115], v212
	ds_read_b128 v[226:229], v213
	v_cvt_pk_bf16_f32 v108, v108, v109
	v_cvt_pk_bf16_f32 v109, v0, v1
	v_mfma_f32_16x16x32_bf16 v[84:87], v[104:107], v[84:87], v[96:99]
	s_waitcnt lgkmcnt(1)
	v_pk_mul_f32 v[0:1], v[34:35], v[114:115]
	s_waitcnt lgkmcnt(0)
	v_pk_mul_f32 v[228:229], v[30:31], v[228:229]
	v_pk_mul_f32 v[114:115], v[28:29], v[226:227]
	v_mfma_f32_16x16x32_bf16 v[80:83], v[116:119], v[80:83], v[88:91]
	v_cvt_pk_bf16_f32 v114, v114, v115
	v_cvt_pk_bf16_f32 v115, v228, v229
	ds_read_b128 v[226:229], v214
	ds_read_b64_tr_b16 v[232:233], v198 offset:57600
	ds_read_b64_tr_b16 v[230:231], v198 offset:53248
	ds_read_b64_tr_b16 v[234:235], v198 offset:53280
	v_pk_mul_f32 v[112:113], v[32:33], v[112:113]
	s_waitcnt lgkmcnt(3)
	v_pk_mul_f32 v[58:59], v[58:59], v[228:229]
	v_pk_mul_f32 v[56:57], v[56:57], v[226:227]
	ds_read_b128 v[226:229], v215
	ds_read_b64_tr_b16 v[236:237], v198 offset:57632
	s_waitcnt lgkmcnt(3)
	v_mfma_f32_16x16x32_bf16 v[56:59], v[230:233], v[92:95], v[56:59]
	v_cvt_pk_bf16_f32 v112, v112, v113
	v_cvt_pk_bf16_f32 v113, v0, v1
	s_waitcnt lgkmcnt(1)
	v_pk_mul_f32 v[54:55], v[54:55], v[228:229]
	v_pk_mul_f32 v[52:53], v[52:53], v[226:227]
	ds_read_b128 v[226:229], v216
	ds_read_b64_tr_b16 v[230:231], v198 offset:53312
	ds_read_b64_tr_b16 v[232:233], v198 offset:57664
	v_mfma_f32_16x16x32_bf16 v[76:79], v[116:119], v[76:79], v[84:87]
	v_add_u32_e32 v0, 32, v190
	s_waitcnt lgkmcnt(2)
	v_pk_mul_f32 v[50:51], v[50:51], v[228:229]
	v_pk_mul_f32 v[48:49], v[48:49], v[226:227]
	v_mfma_f32_16x16x32_bf16 v[72:75], v[108:111], v[72:75], v[80:83]
	v_add_u32_e32 v3, s74, v3
	v_cndmask_b32_e64 v3, v3, v0, s[4:5]
	v_xor_b32_e32 v0, 0xffffffcf, v190
	s_waitcnt lgkmcnt(0)
	v_mfma_f32_16x16x32_bf16 v[48:51], v[230:233], v[92:95], v[48:51]
	ds_read_b128 v[226:229], v217
	ds_read_b64_tr_b16 v[230:231], v198 offset:53344
	ds_read_b64_tr_b16 v[232:233], v198 offset:57696
	v_add_u32_e32 v1, 48, v190
	v_add_u32_e32 v0, s74, v0
	s_waitcnt lgkmcnt(2)
	v_pk_mul_f32 v[46:47], v[46:47], v[228:229]
	v_pk_mul_f32 v[44:45], v[44:45], v[226:227]
	v_mfma_f32_16x16x32_bf16 v[68:71], v[108:111], v[68:71], v[76:79]
	v_add_u32_e32 v190, 64, v190
	s_waitcnt lgkmcnt(0)
	v_mfma_f32_16x16x32_bf16 v[44:47], v[230:233], v[92:95], v[44:47]
	ds_read_b128 v[226:229], v218
	ds_read_b64_tr_b16 v[230:231], v198 offset:53376
	ds_read_b64_tr_b16 v[232:233], v198 offset:57728
	s_waitcnt lgkmcnt(2)
	v_pk_mul_f32 v[42:43], v[42:43], v[228:229]
	v_pk_mul_f32 v[40:41], v[40:41], v[226:227]
	v_mfma_f32_16x16x32_bf16 v[60:63], v[112:115], v[60:63], v[72:75]
	s_waitcnt lgkmcnt(0)
	v_mfma_f32_16x16x32_bf16 v[40:43], v[230:233], v[92:95], v[40:43]
	ds_read_b128 v[226:229], v219
	ds_read_b64_tr_b16 v[230:231], v198 offset:53408
	ds_read_b64_tr_b16 v[232:233], v198 offset:57760
	s_waitcnt lgkmcnt(2)
	v_pk_mul_f32 v[38:39], v[38:39], v[228:229]
	v_pk_mul_f32 v[36:37], v[36:37], v[226:227]
	v_mfma_f32_16x16x32_bf16 v[64:67], v[112:115], v[64:67], v[68:71]
	s_waitcnt lgkmcnt(0)
	v_mfma_f32_16x16x32_bf16 v[36:39], v[230:233], v[92:95], v[36:39]
	ds_read_b128 v[226:229], v220
	ds_read_b64_tr_b16 v[230:231], v198 offset:53440
	ds_read_b64_tr_b16 v[232:233], v198 offset:57792
	v_cndmask_b32_e64 v68, v0, v1, s[4:5]
	v_cvt_pk_bf16_f32 v1, v62, v63
	s_waitcnt lgkmcnt(2)
	v_pk_mul_f32 v[34:35], v[34:35], v[228:229]
	v_pk_mul_f32 v[32:33], v[32:33], v[226:227]
	v_add_u32_e32 v62, s73, v3
	v_ashrrev_i32_e32 v63, 31, v62
	s_waitcnt lgkmcnt(0)
	v_mfma_f32_16x16x32_bf16 v[32:35], v[230:233], v[92:95], v[32:35]
	ds_read_b128 v[226:229], v221
	ds_read_b64_tr_b16 v[230:231], v198 offset:53472
	ds_read_b64_tr_b16 v[232:233], v198 offset:57824
	v_lshlrev_b64 v[62:63], 11, v[62:63]
	v_cvt_pk_bf16_f32 v0, v60, v61
	s_waitcnt lgkmcnt(2)
	v_pk_mul_f32 v[30:31], v[30:31], v[228:229]
	v_pk_mul_f32 v[28:29], v[28:29], v[226:227]
	v_lshl_add_u64 v[62:63], v[186:187], 0, v[62:63]
	v_mfma_f32_16x16x32_bf16 v[52:55], v[234:237], v[92:95], v[52:55]
	global_store_dwordx2 v[62:63], v[0:1], off
	v_add_u32_e32 v0, s73, v68
	v_ashrrev_i32_e32 v1, 31, v0
	s_waitcnt lgkmcnt(0)
	v_mfma_f32_16x16x32_bf16 v[28:31], v[230:233], v[92:95], v[28:31]
	v_lshlrev_b64 v[0:1], 11, v[0:1]
	v_cvt_pk_bf16_f32 v60, v64, v65
	v_cvt_pk_bf16_f32 v61, v66, v67
	v_lshl_add_u64 v[0:1], v[186:187], 0, v[0:1]
	global_store_dwordx2 v[0:1], v[60:61], off
	s_cbranch_scc1 .LBB0_862

.LBB0_859:
	s_or_b64 exec, exec, s[96:97]
	s_add_i32 s78, s77, -1
	s_min_i32 s16, s78, s3
	s_lshl_b32 s16, s16, 5
	v_or_b32_e32 v0, s16, v191
	v_xad_u32 v1, v0, -1, s74
	v_cndmask_b32_e64 v0, v1, v0, s[4:5]
	v_add_u32_e32 v1, s16, v192
	v_xad_u32 v3, v1, -1, s74
	v_add_u32_e32 v0, s73, v0
	v_cndmask_b32_e64 v3, v3, v1, s[4:5]
	v_ashrrev_i32_e32 v1, 31, v0
	s_waitcnt vmcnt(2)
	ds_write_b128 v197, v[8:11] offset:26112
	v_mad_i64_i32 v[8:9], s[16:17], v0, s89, v[180:181]
	v_lshlrev_b64 v[0:1], 11, v[0:1]
	v_lshl_add_u64 v[0:1], v[182:183], 0, v[0:1]
	global_load_dwordx4 v[16:19], v[8:9], off
	global_load_dwordx4 v[24:27], v[0:1], off
	v_add_u32_e32 v0, s73, v3
	v_mad_i64_i32 v[0:1], s[16:17], v0, s89, v[184:185]
	global_load_dwordx4 v[8:11], v[0:1], off
	v_add_u32_e32 v0, 0x1000, v200
	v_add_u32_e32 v1, 0x3000, v201
	s_waitcnt lgkmcnt(0)
	s_barrier
	ds_read_b64_tr_b16 v[92:93], v199 offset:26112
	ds_read_b64_tr_b16 v[94:95], v199 offset:30464
	ds_read_b64 v[88:89], v200
	ds_read_b64 v[90:91], v200 offset:32
	ds_read_b64 v[80:81], v200 offset:64
	ds_read_b64 v[82:83], v200 offset:96
	ds_read_b64 v[72:73], v200 offset:128
	ds_read_b64 v[74:75], v200 offset:160
	ds_read_b64 v[60:61], v200 offset:192
	ds_read_b64 v[62:63], v200 offset:224
	ds_read_b64 v[84:85], v0 offset:256
	ds_read_b64 v[86:87], v0 offset:288
	ds_read_b64 v[76:77], v0 offset:320
	ds_read_b64 v[78:79], v0 offset:352
	ds_read_b64 v[68:69], v0 offset:384
	ds_read_b64 v[70:71], v0 offset:416
	ds_read_b64 v[64:65], v0 offset:448
	ds_read_b64 v[66:67], v0 offset:480
	ds_read_b64 v[100:101], v1 offset:768
	ds_read_b64 v[102:103], v1 offset:800
	v_add_u32_e32 v0, 0x2000, v201
	ds_read_b64 v[96:97], v0 offset:512
	ds_read_b64 v[98:99], v0 offset:544
	ds_read_b64 v[108:109], v0 offset:576
	ds_read_b64 v[110:111], v0 offset:608
	ds_read_b64 v[112:113], v1 offset:832
	ds_read_b64 v[114:115], v1 offset:864
	s_waitcnt lgkmcnt(6)
	v_mfma_f32_16x16x32_bf16 v[100:103], v[100:103], v[84:87], 0
	s_waitcnt lgkmcnt(4)
	v_mfma_f32_16x16x32_bf16 v[104:107], v[96:99], v[88:91], 0
	s_waitcnt lgkmcnt(0)
	v_mfma_f32_16x16x32_bf16 v[100:103], v[112:115], v[76:79], v[100:103]
	ds_read_b64 v[112:113], v0 offset:640
	ds_read_b64 v[114:115], v0 offset:672
	ds_read_b64 v[116:117], v1 offset:896
	ds_read_b64 v[118:119], v1 offset:928
	v_mfma_f32_16x16x32_bf16 v[104:107], v[108:111], v[80:83], v[104:107]
	s_waitcnt lgkmcnt(0)
	v_mfma_f32_16x16x32_bf16 v[100:103], v[116:119], v[68:71], v[100:103]
	ds_read_b64 v[116:117], v0 offset:704
	ds_read_b64 v[118:119], v0 offset:736
	ds_read_b64 v[226:227], v1 offset:960
	ds_read_b64 v[228:229], v1 offset:992
	v_mov_b32_e32 v0, s93
	v_mfma_f32_16x16x32_bf16 v[96:99], v[96:99], v[84:87], 0
	v_mfma_f32_16x16x32_bf16 v[104:107], v[112:115], v[72:75], v[104:107]
	v_mfma_f32_16x16x32_bf16 v[96:99], v[108:111], v[76:79], v[96:99]
	s_waitcnt lgkmcnt(2)
	v_mfma_f32_16x16x32_bf16 v[104:107], v[116:119], v[60:63], v[104:107]
	s_waitcnt lgkmcnt(0)
	v_mfma_f32_16x16x32_bf16 v[100:103], v[226:229], v[64:67], v[100:103]
	v_mov_b32_e32 v226, s93
	s_nop 4
	v_cndmask_b32_e64 v0, v104, v0, s[8:9]
	v_cndmask_b32_e64 v0, v0, v104, s[10:11]
	v_mfma_f32_16x16x32_bf16 v[96:99], v[112:115], v[68:71], v[96:99]
	v_cndmask_b32_e64 v3, v106, 0, s[12:13]
	v_cndmask_b32_e64 v1, v100, v226, s[8:9]
	v_cndmask_b32_e64 v100, v1, v100, s[10:11]
	v_cndmask_b32_e64 v1, 0, v105, s[10:11]
	v_cndmask_b32_e64 v104, v107, 0, s[14:15]
	v_cvt_pk_bf16_f32 v0, v0, v1
	v_cvt_pk_bf16_f32 v1, v3, v104
	ds_read_b128 v[104:107], v202 offset:35328
	ds_read_b128 v[108:111], v202 offset:35392
	v_mfma_f32_16x16x32_bf16 v[96:99], v[116:119], v[64:67], v[96:99]
	v_cndmask_b32_e64 v101, 0, v101, s[10:11]
	v_cndmask_b32_e64 v102, v102, 0, s[12:13]
	v_cndmask_b32_e64 v103, v103, 0, s[14:15]
	v_mov_b32_e32 v3, v2
	s_waitcnt lgkmcnt(0)
	v_pk_mul_f32 v[110:111], v[54:55], v[110:111]
	s_nop 1
	v_cvt_pk_bf16_f32 v96, v96, v97
	v_cvt_pk_bf16_f32 v97, v98, v99
	v_cvt_pk_bf16_f32 v98, v100, v101
	v_cvt_pk_bf16_f32 v99, v102, v103
	v_mfma_f32_16x16x32_bf16 v[100:103], v[92:95], v[0:3], 0
	v_mul_f32_e64 v0, v58, v106
	v_mul_f32_e64 v1, v59, v107
	v_pk_mul_f32 v[106:107], v[52:53], v[108:109]
	v_pk_mul_f32 v[104:105], v[56:57], v[104:105]
	v_cvt_pk_bf16_f32 v106, v106, v107
	v_cvt_pk_bf16_f32 v107, v110, v111
	ds_read_b128 v[108:111], v202 offset:35456
	ds_read_b128 v[112:115], v202 offset:35520
	v_cvt_pk_bf16_f32 v104, v104, v105
	v_cvt_pk_bf16_f32 v105, v0, v1
	v_mfma_f32_16x16x32_bf16 v[96:99], v[92:95], v[96:99], 0
	s_waitcnt lgkmcnt(1)
	v_pk_mul_f32 v[0:1], v[50:51], v[110:111]
	v_pk_mul_f32 v[108:109], v[48:49], v[108:109]
	s_waitcnt lgkmcnt(0)
	v_pk_mul_f32 v[110:111], v[46:47], v[114:115]
	v_pk_mul_f32 v[112:113], v[44:45], v[112:113]
	v_cvt_pk_bf16_f32 v116, v108, v109
	v_cvt_pk_bf16_f32 v118, v112, v113
	v_cvt_pk_bf16_f32 v119, v110, v111
	ds_read_b128 v[108:111], v202 offset:35584
	ds_read_b128 v[112:115], v202 offset:35648
	v_cvt_pk_bf16_f32 v117, v0, v1
	v_mfma_f32_16x16x32_bf16 v[88:91], v[104:107], v[88:91], v[100:103]
	v_cndmask_b32_e64 v3, v222, v190, s[4:5]
	s_waitcnt lgkmcnt(1)
	v_pk_mul_f32 v[0:1], v[42:43], v[110:111]
	s_waitcnt lgkmcnt(0)
	v_pk_mul_f32 v[114:115], v[38:39], v[114:115]
	v_pk_mul_f32 v[110:111], v[36:37], v[112:113]
	v_pk_mul_f32 v[108:109], v[40:41], v[108:109]
	v_cvt_pk_bf16_f32 v110, v110, v111
	v_cvt_pk_bf16_f32 v111, v114, v115
	ds_read_b128 v[112:115], v202 offset:35712
	ds_read_b128 v[226:229], v202 offset:35776
	v_cvt_pk_bf16_f32 v108, v108, v109
	v_cvt_pk_bf16_f32 v109, v0, v1
	v_mfma_f32_16x16x32_bf16 v[84:87], v[104:107], v[84:87], v[96:99]
	s_waitcnt lgkmcnt(1)
	v_pk_mul_f32 v[0:1], v[34:35], v[114:115]
	s_waitcnt lgkmcnt(0)
	v_pk_mul_f32 v[228:229], v[30:31], v[228:229]
	v_pk_mul_f32 v[114:115], v[28:29], v[226:227]
	v_mfma_f32_16x16x32_bf16 v[80:83], v[116:119], v[80:83], v[88:91]
	v_cvt_pk_bf16_f32 v114, v114, v115
	v_cvt_pk_bf16_f32 v115, v228, v229
	ds_read_b128 v[226:229], v202 offset:34816
	ds_read_b64_tr_b16 v[232:233], v198 offset:21760
	ds_read_b64_tr_b16 v[230:231], v198 offset:17408
	ds_read_b64_tr_b16 v[234:235], v198 offset:17440
	v_pk_mul_f32 v[112:113], v[32:33], v[112:113]
	s_waitcnt lgkmcnt(3)
	v_pk_mul_f32 v[58:59], v[58:59], v[228:229]
	v_pk_mul_f32 v[56:57], v[56:57], v[226:227]
	ds_read_b128 v[226:229], v202 offset:34880
	ds_read_b64_tr_b16 v[236:237], v198 offset:21792
	s_waitcnt lgkmcnt(3)
	v_mfma_f32_16x16x32_bf16 v[56:59], v[230:233], v[92:95], v[56:59]
	v_cvt_pk_bf16_f32 v112, v112, v113
	v_cvt_pk_bf16_f32 v113, v0, v1
	s_waitcnt lgkmcnt(1)
	v_pk_mul_f32 v[54:55], v[54:55], v[228:229]
	v_pk_mul_f32 v[52:53], v[52:53], v[226:227]
	ds_read_b128 v[226:229], v202 offset:34944
	ds_read_b64_tr_b16 v[230:231], v198 offset:17472
	ds_read_b64_tr_b16 v[232:233], v198 offset:21824
	v_mfma_f32_16x16x32_bf16 v[76:79], v[116:119], v[76:79], v[84:87]
	v_xor_b32_e32 v1, 0xffffffef, v190
	s_waitcnt lgkmcnt(2)
	v_pk_mul_f32 v[50:51], v[50:51], v[228:229]
	v_pk_mul_f32 v[48:49], v[48:49], v[226:227]
	v_mfma_f32_16x16x32_bf16 v[72:75], v[108:111], v[72:75], v[80:83]
	v_add_u32_e32 v0, 16, v190
	v_add_u32_e32 v1, s74, v1
	s_waitcnt lgkmcnt(0)
	v_mfma_f32_16x16x32_bf16 v[48:51], v[230:233], v[92:95], v[48:51]
	ds_read_b128 v[226:229], v202 offset:35008
	ds_read_b64_tr_b16 v[230:231], v198 offset:17504
	ds_read_b64_tr_b16 v[232:233], v198 offset:21856
	s_waitcnt lgkmcnt(2)
	v_pk_mul_f32 v[46:47], v[46:47], v[228:229]
	v_pk_mul_f32 v[44:45], v[44:45], v[226:227]
	v_mfma_f32_16x16x32_bf16 v[68:71], v[108:111], v[68:71], v[76:79]
	s_waitcnt lgkmcnt(0)
	v_mfma_f32_16x16x32_bf16 v[44:47], v[230:233], v[92:95], v[44:47]
	ds_read_b128 v[226:229], v202 offset:35072
	ds_read_b64_tr_b16 v[230:231], v198 offset:17536
	ds_read_b64_tr_b16 v[232:233], v198 offset:21888
	s_waitcnt lgkmcnt(2)
	v_pk_mul_f32 v[42:43], v[42:43], v[228:229]
	v_pk_mul_f32 v[40:41], v[40:41], v[226:227]
	v_mfma_f32_16x16x32_bf16 v[60:63], v[112:115], v[60:63], v[72:75]
	s_waitcnt lgkmcnt(0)
	v_mfma_f32_16x16x32_bf16 v[40:43], v[230:233], v[92:95], v[40:43]
	ds_read_b128 v[226:229], v202 offset:35136
	ds_read_b64_tr_b16 v[230:231], v198 offset:17568
	ds_read_b64_tr_b16 v[232:233], v198 offset:21920
	s_waitcnt lgkmcnt(2)
	v_pk_mul_f32 v[38:39], v[38:39], v[228:229]
	v_pk_mul_f32 v[36:37], v[36:37], v[226:227]
	v_mfma_f32_16x16x32_bf16 v[64:67], v[112:115], v[64:67], v[68:71]
	s_waitcnt lgkmcnt(0)
	v_mfma_f32_16x16x32_bf16 v[36:39], v[230:233], v[92:95], v[36:39]
	ds_read_b128 v[226:229], v202 offset:35200
	ds_read_b64_tr_b16 v[230:231], v198 offset:17600
	ds_read_b64_tr_b16 v[232:233], v198 offset:21952
	v_cndmask_b32_e64 v68, v1, v0, s[4:5]
	v_cvt_pk_bf16_f32 v1, v62, v63
	s_waitcnt lgkmcnt(2)
	v_pk_mul_f32 v[34:35], v[34:35], v[228:229]
	v_pk_mul_f32 v[32:33], v[32:33], v[226:227]
	v_add_u32_e32 v62, s73, v3
	v_ashrrev_i32_e32 v63, 31, v62
	s_waitcnt lgkmcnt(0)
	v_mfma_f32_16x16x32_bf16 v[32:35], v[230:233], v[92:95], v[32:35]
	ds_read_b128 v[226:229], v202 offset:35264
	ds_read_b64_tr_b16 v[230:231], v198 offset:17632
	ds_read_b64_tr_b16 v[232:233], v198 offset:21984
	v_lshlrev_b64 v[62:63], 11, v[62:63]
	v_cvt_pk_bf16_f32 v0, v60, v61
	s_waitcnt lgkmcnt(2)
	v_pk_mul_f32 v[30:31], v[30:31], v[228:229]
	v_pk_mul_f32 v[28:29], v[28:29], v[226:227]
	v_lshl_add_u64 v[62:63], v[186:187], 0, v[62:63]
	v_mfma_f32_16x16x32_bf16 v[52:55], v[234:237], v[92:95], v[52:55]
	global_store_dwordx2 v[62:63], v[0:1], off
	v_add_u32_e32 v0, s73, v68
	v_ashrrev_i32_e32 v1, 31, v0
	s_waitcnt lgkmcnt(0)
	v_mfma_f32_16x16x32_bf16 v[28:31], v[230:233], v[92:95], v[28:31]
	v_lshlrev_b64 v[0:1], 11, v[0:1]
	v_cvt_pk_bf16_f32 v60, v64, v65
	v_cvt_pk_bf16_f32 v61, v66, v67
	v_lshl_add_u64 v[0:1], v[186:187], 0, v[0:1]
	global_store_dwordx2 v[0:1], v[60:61], off
	s_and_saveexec_b64 s[96:97], vcc
	s_cbranch_execz .LBB0_854
	v_cvt_f32_f16_e32 v76, v20
	v_cvt_f32_f16_sdwa v75, v20 dst_sel:DWORD dst_unused:UNUSED_PAD src0_sel:WORD_1
	v_cvt_f32_f16_e32 v74, v21
	v_cvt_f32_f16_sdwa v73, v21 dst_sel:DWORD dst_unused:UNUSED_PAD src0_sel:WORD_1
	v_add_f32_dpp v0, v76, v76 row_shr:1 row_mask:0xf bank_mask:0xf bound_ctrl:1
	v_add_f32_dpp v1, v75, v75 row_shr:1 row_mask:0xf bank_mask:0xf bound_ctrl:1
	v_mov_b32_e32 v62, v2
	v_add_f32_dpp v0, v0, v0 row_shr:2 row_mask:0xf bank_mask:0xf bound_ctrl:1
	v_add_f32_dpp v1, v1, v1 row_shr:2 row_mask:0xf bank_mask:0xf bound_ctrl:1
	v_cvt_f32_f16_e32 v72, v22
	v_add_f32_dpp v0, v0, v0 row_shr:4 row_mask:0xf bank_mask:0xf bound_ctrl:1
	v_add_f32_dpp v20, v74, v74 row_shr:1 row_mask:0xf bank_mask:0xf bound_ctrl:1
	v_add_f32_dpp v1, v1, v1 row_shr:4 row_mask:0xf bank_mask:0xf bound_ctrl:1
	v_add_f32_dpp v0, v0, v0 row_shr:8 row_mask:0xf bank_mask:0xf bound_ctrl:1
	v_add_f32_dpp v20, v20, v20 row_shr:2 row_mask:0xf bank_mask:0xf bound_ctrl:1
	v_add_f32_dpp v1, v1, v1 row_shr:8 row_mask:0xf bank_mask:0xf bound_ctrl:1
	v_mov_b32_dpp v62, v0 row_bcast:15 row_mask:0xa bank_mask:0xf
	v_add_f32_e32 v78, v0, v62
	v_mov_b32_e32 v0, v2
	v_cvt_f32_f16_sdwa v71, v22 dst_sel:DWORD dst_unused:UNUSED_PAD src0_sel:WORD_1
	v_add_f32_dpp v21, v73, v73 row_shr:1 row_mask:0xf bank_mask:0xf bound_ctrl:1
	v_add_f32_dpp v20, v20, v20 row_shr:4 row_mask:0xf bank_mask:0xf bound_ctrl:1
	v_mov_b32_dpp v0, v1 row_bcast:15 row_mask:0xa bank_mask:0xf
	v_add_f32_dpp v21, v21, v21 row_shr:2 row_mask:0xf bank_mask:0xf bound_ctrl:1
	v_add_f32_dpp v20, v20, v20 row_shr:8 row_mask:0xf bank_mask:0xf bound_ctrl:1
	v_add_f32_e32 v79, v1, v0
	v_mov_b32_e32 v0, v2
	v_cvt_f32_f16_e32 v70, v23
	v_add_f32_dpp v22, v72, v72 row_shr:1 row_mask:0xf bank_mask:0xf bound_ctrl:1
	v_add_f32_dpp v21, v21, v21 row_shr:4 row_mask:0xf bank_mask:0xf bound_ctrl:1
	v_mov_b32_dpp v0, v20 row_bcast:15 row_mask:0xa bank_mask:0xf
	v_add_f32_dpp v22, v22, v22 row_shr:2 row_mask:0xf bank_mask:0xf bound_ctrl:1
	v_add_f32_dpp v21, v21, v21 row_shr:8 row_mask:0xf bank_mask:0xf bound_ctrl:1
	v_add_f32_e32 v80, v20, v0
	v_mov_b32_e32 v0, v2
	v_cvt_f32_f16_sdwa v3, v23 dst_sel:DWORD dst_unused:UNUSED_PAD src0_sel:WORD_1
	v_add_f32_dpp v23, v71, v71 row_shr:1 row_mask:0xf bank_mask:0xf bound_ctrl:1
	v_add_f32_dpp v22, v22, v22 row_shr:4 row_mask:0xf bank_mask:0xf bound_ctrl:1
	v_mov_b32_dpp v0, v21 row_bcast:15 row_mask:0xa bank_mask:0xf
	v_add_f32_dpp v23, v23, v23 row_shr:2 row_mask:0xf bank_mask:0xf bound_ctrl:1
	v_add_f32_dpp v22, v22, v22 row_shr:8 row_mask:0xf bank_mask:0xf bound_ctrl:1
	v_add_f32_e32 v81, v21, v0
	v_mov_b32_e32 v0, v2
	v_add_f32_dpp v60, v70, v70 row_shr:1 row_mask:0xf bank_mask:0xf bound_ctrl:1
	v_add_f32_dpp v23, v23, v23 row_shr:4 row_mask:0xf bank_mask:0xf bound_ctrl:1
	v_mov_b32_dpp v0, v22 row_bcast:15 row_mask:0xa bank_mask:0xf
	ds_bpermute_b32 v1, v193, v78
	v_add_f32_dpp v60, v60, v60 row_shr:2 row_mask:0xf bank_mask:0xf bound_ctrl:1
	v_add_f32_dpp v23, v23, v23 row_shr:8 row_mask:0xf bank_mask:0xf bound_ctrl:1
	v_add_f32_e32 v77, v22, v0
	v_mov_b32_e32 v0, v2
	v_add_f32_dpp v60, v60, v60 row_shr:4 row_mask:0xf bank_mask:0xf bound_ctrl:1
	v_add_f32_dpp v61, v3, v3 row_shr:1 row_mask:0xf bank_mask:0xf bound_ctrl:1
	v_mov_b32_dpp v0, v23 row_bcast:15 row_mask:0xa bank_mask:0xf
	v_add_f32_dpp v60, v60, v60 row_shr:8 row_mask:0xf bank_mask:0xf bound_ctrl:1
	v_add_f32_e32 v82, v23, v0
	v_mov_b32_e32 v0, v2
	v_add_f32_dpp v61, v61, v61 row_shr:2 row_mask:0xf bank_mask:0xf bound_ctrl:1
	ds_bpermute_b32 v22, v193, v80
	v_mov_b32_dpp v0, v60 row_bcast:15 row_mask:0xa bank_mask:0xf
	v_add_f32_e32 v83, v60, v0
	s_waitcnt lgkmcnt(1)
	v_sub_f32_e32 v0, v78, v1
	ds_bpermute_b32 v1, v193, v79
	v_med3_f32 v0, v0, s69, v189
	v_add_f32_dpp v61, v61, v61 row_shr:4 row_mask:0xf bank_mask:0xf bound_ctrl:1
	v_mul_f32_e32 v0, 0x3fb8aa3b, v0
	v_exp_f32_e32 v20, v0
	v_add_f32_dpp v61, v61, v61 row_shr:8 row_mask:0xf bank_mask:0xf bound_ctrl:1
	v_mov_b32_e32 v0, v2
	s_waitcnt lgkmcnt(0)
	v_sub_f32_e32 v1, v79, v1
	v_med3_f32 v1, v1, s69, v189
	v_mov_b32_dpp v0, v61 row_bcast:15 row_mask:0xa bank_mask:0xf
	v_add_f32_e32 v84, v61, v0
	v_mul_f32_e32 v1, 0x3fb8aa3b, v1
	v_exp_f32_e32 v21, v1
	ds_bpermute_b32 v1, v193, v81
	ds_bpermute_b32 v62, v193, v77
	ds_bpermute_b32 v63, v193, v82
	ds_bpermute_b32 v64, v193, v83
	ds_bpermute_b32 v65, v193, v84
	v_sub_f32_e32 v22, v80, v22
	s_waitcnt lgkmcnt(4)
	v_sub_f32_e32 v1, v81, v1
	s_waitcnt lgkmcnt(3)
	v_sub_f32_e32 v62, v77, v62
	s_waitcnt lgkmcnt(2)
	v_sub_f32_e32 v63, v82, v63
	s_waitcnt lgkmcnt(1)
	v_sub_f32_e32 v64, v83, v64
	s_waitcnt lgkmcnt(0)
	v_sub_f32_e32 v65, v84, v65
	v_med3_f32 v22, v22, s69, v189
	v_med3_f32 v1, v1, s69, v189
	v_med3_f32 v62, v62, s69, v189
	v_med3_f32 v63, v63, s69, v189
	v_med3_f32 v64, v64, s69, v189
	v_med3_f32 v65, v65, s69, v189
	v_mul_f32_e32 v22, 0x3fb8aa3b, v22
	v_mul_f32_e32 v1, 0x3fb8aa3b, v1
	v_mul_f32_e32 v62, 0x3fb8aa3b, v62
	v_mul_f32_e32 v63, 0x3fb8aa3b, v63
	v_mul_f32_e32 v64, 0x3fb8aa3b, v64
	v_mul_f32_e32 v65, 0x3fb8aa3b, v65
	v_exp_f32_e32 v60, v22
	v_exp_f32_e32 v61, v1
	v_exp_f32_e32 v62, v62
	v_exp_f32_e32 v63, v63
	v_exp_f32_e32 v64, v64
	v_exp_f32_e32 v65, v65
	ds_bpermute_b32 v0, v194, v20
	ds_bpermute_b32 v1, v194, v21
	ds_bpermute_b32 v22, v194, v60
	ds_bpermute_b32 v23, v194, v61
	ds_bpermute_b32 v68, v194, v62
	ds_bpermute_b32 v69, v194, v63
	ds_bpermute_b32 v66, v194, v64
	ds_bpermute_b32 v67, v194, v65
	s_and_saveexec_b64 s[16:17], s[6:7]
	s_cbranch_execz .LBB0_853
	v_mul_f32_e32 v78, 0x3fb8aa3b, v78
	v_mul_f32_e32 v79, 0x3fb8aa3b, v79
	v_mul_f32_e32 v80, 0x3fb8aa3b, v80
	v_mul_f32_e32 v81, 0x3fb8aa3b, v81
	v_exp_f32_e32 v78, v78
	v_exp_f32_e32 v79, v79
	v_exp_f32_e32 v80, v80
	v_exp_f32_e32 v81, v81
	v_mul_f32_e32 v77, 0x3fb8aa3b, v77
	ds_write_b128 v203, v[78:81]
	v_exp_f32_e32 v78, v77
	v_mul_f32_e32 v77, 0x3fb8aa3b, v82
	v_exp_f32_e32 v79, v77
	v_mul_f32_e32 v77, 0x3fb8aa3b, v83
	v_exp_f32_e32 v80, v77
	v_mul_f32_e32 v77, 0x3fb8aa3b, v84
	v_exp_f32_e32 v81, v77
	ds_write_b128 v203, v[78:81] offset:16
	s_branch .LBB0_853

.LBB0_868:
	s_or_b64 exec, exec, s[80:81]
	s_min_i32 s16, s35, s77
	s_lshl_b32 s16, s16, 5
	v_or_b32_e32 v0, s16, v127
	v_xad_u32 v1, v0, -1, s74
	v_cndmask_b32_e64 v0, v1, v0, s[4:5]
	v_add_u32_e32 v1, s16, v128
	v_xad_u32 v3, v1, -1, s74
	v_add_u32_e32 v0, s73, v0
	s_waitcnt vmcnt(8)
	ds_write_b128 v133, v[4:7] offset:61952
	v_cndmask_b32_e64 v3, v3, v1, s[4:5]
	v_ashrrev_i32_e32 v1, 31, v0
	v_mad_i64_i32 v[4:5], s[16:17], v0, s89, v[116:117]
	global_load_dwordx4 v[20:23], v[4:5], off
	v_lshlrev_b64 v[4:5], 10, v[0:1]
	v_lshl_add_u64 v[4:5], v[118:119], 0, v[4:5]
	v_mad_i64_i32 v[0:1], s[16:17], v0, s89, v[120:121]
	global_load_dwordx4 v[28:31], v[4:5], off
	global_load_dwordx4 v[12:15], v[0:1], off
	v_add_u32_e32 v0, s73, v3
	v_mad_i64_i32 v[0:1], s[16:17], v0, s89, v[122:123]
	global_load_dwordx4 v[4:7], v[0:1], off
	v_add_u32_e32 v0, 0x8800, v135
	s_waitcnt lgkmcnt(0)
	s_barrier
	ds_read_b64_tr_b16 v[68:69], v140
	ds_read_b64_tr_b16 v[70:71], v140 offset:4352
	ds_read_b64 v[64:65], v0 offset:1024
	ds_read_b64 v[66:67], v0 offset:1056
	ds_read_b64 v[52:53], v0 offset:1088
	ds_read_b64 v[54:55], v0 offset:1120
	v_add_u32_e32 v0, 0x9000, v135
	ds_read_b64 v[60:61], v0 offset:1280
	ds_read_b64 v[62:63], v0 offset:1312
	ds_read_b64 v[56:57], v0 offset:1344
	ds_read_b64 v[58:59], v0 offset:1376
	v_add_u32_e32 v0, 0xa800, v136
	v_add_u32_e32 v1, 0xb000, v136
	ds_read_b64 v[72:73], v0 offset:1536
	ds_read_b64 v[74:75], v0 offset:1568
	ds_read_b64 v[76:77], v1 offset:1792
	ds_read_b64 v[78:79], v1 offset:1824
	ds_read_b64 v[84:85], v0 offset:1600
	ds_read_b64 v[86:87], v0 offset:1632
	ds_read_b64 v[150:151], v1 offset:1856
	ds_read_b64 v[152:153], v1 offset:1888
	s_waitcnt lgkmcnt(6)
	v_mfma_f32_16x16x32_bf16 v[80:83], v[72:75], v[64:67], 0
	v_mov_b32_e32 v0, s93
	s_add_i32 s35, s35, 2
	v_subrev_u32_e32 v149, 64, v149
	s_waitcnt lgkmcnt(4)
	v_mfma_f32_16x16x32_bf16 v[76:79], v[76:79], v[60:63], 0
	s_cmp_ge_u32 s78, s3
	s_waitcnt lgkmcnt(2)
	v_mfma_f32_16x16x32_bf16 v[80:83], v[84:87], v[52:55], v[80:83]
	s_waitcnt lgkmcnt(0)
	v_mfma_f32_16x16x32_bf16 v[76:79], v[150:153], v[56:59], v[76:79]
	v_mov_b32_e32 v150, s93
	s_nop 4
	v_cndmask_b32_e64 v0, v80, v0, s[8:9]
	v_cndmask_b32_e64 v0, v0, v80, s[10:11]
	v_mfma_f32_16x16x32_bf16 v[72:75], v[72:75], v[60:63], 0
	v_cndmask_b32_e64 v3, v82, 0, s[12:13]
	v_cndmask_b32_e64 v1, v76, v150, s[8:9]
	v_cndmask_b32_e64 v76, v1, v76, s[10:11]
	v_cndmask_b32_e64 v1, 0, v81, s[10:11]
	v_cndmask_b32_e64 v80, v83, 0, s[14:15]
	v_mfma_f32_16x16x32_bf16 v[72:75], v[84:87], v[56:59], v[72:75]
	v_cvt_pk_bf16_f32 v0, v0, v1
	v_cvt_pk_bf16_f32 v1, v3, v80
	ds_read_b128 v[80:83], v141
	ds_read_b128 v[84:87], v142
	v_cndmask_b32_e64 v77, 0, v77, s[10:11]
	v_cndmask_b32_e64 v78, v78, 0, s[12:13]
	v_cndmask_b32_e64 v79, v79, 0, s[14:15]
	v_mov_b32_e32 v3, v2
	v_cvt_pk_bf16_f32 v72, v72, v73
	v_cvt_pk_bf16_f32 v73, v74, v75
	v_cvt_pk_bf16_f32 v74, v76, v77
	v_cvt_pk_bf16_f32 v75, v78, v79
	v_mfma_f32_16x16x32_bf16 v[76:79], v[68:71], v[0:3], 0
	s_waitcnt lgkmcnt(1)
	v_pk_mul_f32 v[0:1], v[50:51], v[82:83]
	s_waitcnt lgkmcnt(0)
	v_pk_mul_f32 v[86:87], v[46:47], v[86:87]
	v_pk_mul_f32 v[82:83], v[44:45], v[84:85]
	v_pk_mul_f32 v[80:81], v[48:49], v[80:81]
	v_cvt_pk_bf16_f32 v82, v82, v83
	v_cvt_pk_bf16_f32 v83, v86, v87
	ds_read_b128 v[84:87], v143
	ds_read_b128 v[150:153], v144
	v_cvt_pk_bf16_f32 v80, v80, v81
	v_cvt_pk_bf16_f32 v81, v0, v1
	v_mfma_f32_16x16x32_bf16 v[72:75], v[68:71], v[72:75], 0
	s_waitcnt lgkmcnt(1)
	v_pk_mul_f32 v[0:1], v[42:43], v[86:87]
	s_waitcnt lgkmcnt(0)
	v_pk_mul_f32 v[152:153], v[38:39], v[152:153]
	v_pk_mul_f32 v[86:87], v[36:37], v[150:151]
	v_pk_mul_f32 v[84:85], v[40:41], v[84:85]
	v_cvt_pk_bf16_f32 v86, v86, v87
	v_cvt_pk_bf16_f32 v87, v152, v153
	ds_read_b128 v[150:153], v145
	ds_read_b64_tr_b16 v[156:157], v138 offset:55552
	ds_read_b64_tr_b16 v[154:155], v138 offset:53248
	ds_read_b64_tr_b16 v[158:159], v138 offset:53280
	v_cvt_pk_bf16_f32 v84, v84, v85
	s_waitcnt lgkmcnt(3)
	v_pk_mul_f32 v[50:51], v[50:51], v[152:153]
	v_pk_mul_f32 v[48:49], v[48:49], v[150:151]
	ds_read_b128 v[150:153], v146
	ds_read_b64_tr_b16 v[160:161], v138 offset:55584
	v_cvt_pk_bf16_f32 v85, v0, v1
	v_mfma_f32_16x16x32_bf16 v[64:67], v[80:83], v[64:67], v[76:79]
	v_xor_b32_e32 v3, 0xffffffdf, v126
	s_waitcnt lgkmcnt(1)
	v_pk_mul_f32 v[46:47], v[46:47], v[152:153]
	v_pk_mul_f32 v[44:45], v[44:45], v[150:151]
	v_mfma_f32_16x16x32_bf16 v[48:51], v[154:157], v[68:71], v[48:51]
	ds_read_b128 v[150:153], v147
	ds_read_b64_tr_b16 v[154:155], v138 offset:53312
	ds_read_b64_tr_b16 v[156:157], v138 offset:55616
	v_add_u32_e32 v0, 32, v126
	v_add_u32_e32 v3, s74, v3
	v_mfma_f32_16x16x32_bf16 v[60:63], v[80:83], v[60:63], v[72:75]
	s_waitcnt lgkmcnt(2)
	v_pk_mul_f32 v[42:43], v[42:43], v[152:153]
	v_pk_mul_f32 v[40:41], v[40:41], v[150:151]
	v_cndmask_b32_e64 v3, v3, v0, s[4:5]
	v_mfma_f32_16x16x32_bf16 v[52:55], v[84:87], v[52:55], v[64:67]
	v_xor_b32_e32 v0, 0xffffffcf, v126
	v_add_u32_e32 v1, 48, v126
	v_add_u32_e32 v0, s74, v0
	s_waitcnt lgkmcnt(0)
	v_mfma_f32_16x16x32_bf16 v[40:43], v[154:157], v[68:71], v[40:43]
	ds_read_b128 v[150:153], v148
	ds_read_b64_tr_b16 v[154:155], v138 offset:53344
	ds_read_b64_tr_b16 v[156:157], v138 offset:55648
	v_add_u32_e32 v126, 64, v126
	s_waitcnt lgkmcnt(2)
	v_pk_mul_f32 v[38:39], v[38:39], v[152:153]
	v_mfma_f32_16x16x32_bf16 v[56:59], v[84:87], v[56:59], v[60:63]
	v_mul_f32_e64 v36, v36, v150
	v_mul_f32_e64 v37, v37, v151
	s_nop 0
	v_cndmask_b32_e64 v60, v0, v1, s[4:5]
	v_cvt_pk_bf16_f32 v1, v54, v55
	v_add_u32_e32 v54, s73, v3
	v_ashrrev_i32_e32 v55, 31, v54
	v_lshlrev_b64 v[54:55], 11, v[54:55]
	v_cvt_pk_bf16_f32 v0, v52, v53
	v_lshl_add_u64 v[54:55], v[124:125], 0, v[54:55]
	v_mfma_f32_16x16x32_bf16 v[44:47], v[158:161], v[68:71], v[44:47]
	global_store_dwordx2 v[54:55], v[0:1], off offset:1024
	v_add_u32_e32 v0, s73, v60
	v_ashrrev_i32_e32 v1, 31, v0
	s_waitcnt lgkmcnt(0)
	v_mfma_f32_16x16x32_bf16 v[36:39], v[154:157], v[68:71], v[36:39]
	v_lshlrev_b64 v[0:1], 11, v[0:1]
	v_cvt_pk_bf16_f32 v52, v56, v57
	v_cvt_pk_bf16_f32 v53, v58, v59
	v_lshl_add_u64 v[0:1], v[124:125], 0, v[0:1]
	global_store_dwordx2 v[0:1], v[52:53], off offset:1024
	s_cbranch_scc1 .LBB0_876

.LBB0_873:
	s_or_b64 exec, exec, s[80:81]
	s_add_i32 s78, s35, -1
	s_min_i32 s16, s78, s77
	s_lshl_b32 s16, s16, 5
	v_or_b32_e32 v0, s16, v127
	v_xad_u32 v1, v0, -1, s74
	v_cndmask_b32_e64 v0, v1, v0, s[4:5]
	v_add_u32_e32 v1, s16, v128
	v_xad_u32 v3, v1, -1, s74
	v_add_u32_e32 v0, s73, v0
	s_waitcnt vmcnt(3)
	ds_write_b128 v133, v[8:11] offset:26112
	v_cndmask_b32_e64 v3, v3, v1, s[4:5]
	v_ashrrev_i32_e32 v1, 31, v0
	v_mad_i64_i32 v[8:9], s[16:17], v0, s89, v[116:117]
	global_load_dwordx4 v[24:27], v[8:9], off
	v_lshlrev_b64 v[8:9], 10, v[0:1]
	v_lshl_add_u64 v[8:9], v[118:119], 0, v[8:9]
	v_mad_i64_i32 v[0:1], s[16:17], v0, s89, v[120:121]
	global_load_dwordx4 v[32:35], v[8:9], off
	global_load_dwordx4 v[16:19], v[0:1], off
	v_add_u32_e32 v0, s73, v3
	v_mad_i64_i32 v[0:1], s[16:17], v0, s89, v[122:123]
	global_load_dwordx4 v[8:11], v[0:1], off
	v_add_u32_e32 v0, 0x800, v135
	s_waitcnt lgkmcnt(0)
	s_barrier
	ds_read_b64_tr_b16 v[68:69], v134 offset:26112
	ds_read_b64_tr_b16 v[70:71], v134 offset:30464
	ds_read_b64 v[64:65], v135
	ds_read_b64 v[66:67], v135 offset:32
	ds_read_b64 v[52:53], v135 offset:64
	ds_read_b64 v[54:55], v135 offset:96
	ds_read_b64 v[60:61], v0 offset:256
	ds_read_b64 v[62:63], v0 offset:288
	ds_read_b64 v[56:57], v0 offset:320
	ds_read_b64 v[58:59], v0 offset:352
	v_add_u32_e32 v0, 0x2000, v136
	v_add_u32_e32 v1, 0x2800, v136
	ds_read_b64 v[72:73], v0 offset:512
	ds_read_b64 v[74:75], v0 offset:544
	ds_read_b64 v[76:77], v1 offset:768
	ds_read_b64 v[78:79], v1 offset:800
	ds_read_b64 v[84:85], v0 offset:576
	ds_read_b64 v[86:87], v0 offset:608
	ds_read_b64 v[150:151], v1 offset:832
	ds_read_b64 v[152:153], v1 offset:864
	s_waitcnt lgkmcnt(6)
	v_mfma_f32_16x16x32_bf16 v[80:83], v[72:75], v[64:67], 0
	v_mov_b32_e32 v0, s93
	s_waitcnt lgkmcnt(4)
	v_mfma_f32_16x16x32_bf16 v[76:79], v[76:79], v[60:63], 0
	s_waitcnt lgkmcnt(2)
	v_mfma_f32_16x16x32_bf16 v[80:83], v[84:87], v[52:55], v[80:83]
	s_waitcnt lgkmcnt(0)
	v_mfma_f32_16x16x32_bf16 v[76:79], v[150:153], v[56:59], v[76:79]
	v_mov_b32_e32 v150, s93
	s_nop 4
	v_cndmask_b32_e64 v0, v80, v0, s[8:9]
	v_cndmask_b32_e64 v0, v0, v80, s[10:11]
	v_mfma_f32_16x16x32_bf16 v[72:75], v[72:75], v[60:63], 0
	v_cndmask_b32_e64 v3, v82, 0, s[12:13]
	v_cndmask_b32_e64 v1, v76, v150, s[8:9]
	v_cndmask_b32_e64 v76, v1, v76, s[10:11]
	v_cndmask_b32_e64 v1, 0, v81, s[10:11]
	v_cndmask_b32_e64 v80, v83, 0, s[14:15]
	v_mfma_f32_16x16x32_bf16 v[72:75], v[84:87], v[56:59], v[72:75]
	v_cvt_pk_bf16_f32 v0, v0, v1
	v_cvt_pk_bf16_f32 v1, v3, v80
	ds_read_b128 v[80:83], v137 offset:35328
	ds_read_b128 v[84:87], v137 offset:35392
	v_cndmask_b32_e64 v77, 0, v77, s[10:11]
	v_cndmask_b32_e64 v78, v78, 0, s[12:13]
	v_cndmask_b32_e64 v79, v79, 0, s[14:15]
	v_mov_b32_e32 v3, v2
	v_cvt_pk_bf16_f32 v72, v72, v73
	v_cvt_pk_bf16_f32 v73, v74, v75
	v_cvt_pk_bf16_f32 v74, v76, v77
	v_cvt_pk_bf16_f32 v75, v78, v79
	v_mfma_f32_16x16x32_bf16 v[76:79], v[68:71], v[0:3], 0
	s_waitcnt lgkmcnt(1)
	v_pk_mul_f32 v[0:1], v[50:51], v[82:83]
	s_waitcnt lgkmcnt(0)
	v_pk_mul_f32 v[86:87], v[46:47], v[86:87]
	v_pk_mul_f32 v[82:83], v[44:45], v[84:85]
	v_pk_mul_f32 v[80:81], v[48:49], v[80:81]
	v_cvt_pk_bf16_f32 v82, v82, v83
	v_cvt_pk_bf16_f32 v83, v86, v87
	ds_read_b128 v[84:87], v137 offset:35456
	ds_read_b128 v[150:153], v137 offset:35520
	v_cvt_pk_bf16_f32 v80, v80, v81
	v_cvt_pk_bf16_f32 v81, v0, v1
	v_mfma_f32_16x16x32_bf16 v[72:75], v[68:71], v[72:75], 0
	s_waitcnt lgkmcnt(1)
	v_pk_mul_f32 v[0:1], v[42:43], v[86:87]
	s_waitcnt lgkmcnt(0)
	v_pk_mul_f32 v[152:153], v[38:39], v[152:153]
	v_pk_mul_f32 v[86:87], v[36:37], v[150:151]
	v_pk_mul_f32 v[84:85], v[40:41], v[84:85]
	v_cvt_pk_bf16_f32 v86, v86, v87
	v_cvt_pk_bf16_f32 v87, v152, v153
	ds_read_b128 v[150:153], v137 offset:34816
	ds_read_b64_tr_b16 v[156:157], v138 offset:19712
	ds_read_b64_tr_b16 v[154:155], v138 offset:17408
	ds_read_b64_tr_b16 v[158:159], v138 offset:17440
	v_cvt_pk_bf16_f32 v84, v84, v85
	s_waitcnt lgkmcnt(3)
	v_pk_mul_f32 v[50:51], v[50:51], v[152:153]
	v_pk_mul_f32 v[48:49], v[48:49], v[150:151]
	ds_read_b128 v[150:153], v137 offset:34880
	ds_read_b64_tr_b16 v[160:161], v138 offset:19744
	v_cvt_pk_bf16_f32 v85, v0, v1
	v_mfma_f32_16x16x32_bf16 v[64:67], v[80:83], v[64:67], v[76:79]
	v_xor_b32_e32 v1, 0xffffffef, v126
	s_waitcnt lgkmcnt(1)
	v_pk_mul_f32 v[46:47], v[46:47], v[152:153]
	v_pk_mul_f32 v[44:45], v[44:45], v[150:151]
	v_mfma_f32_16x16x32_bf16 v[48:51], v[154:157], v[68:71], v[48:51]
	ds_read_b128 v[150:153], v137 offset:34944
	ds_read_b64_tr_b16 v[154:155], v138 offset:17472
	ds_read_b64_tr_b16 v[156:157], v138 offset:19776
	v_add_u32_e32 v0, 16, v126
	v_cndmask_b32_e64 v3, v149, v126, s[4:5]
	v_mfma_f32_16x16x32_bf16 v[60:63], v[80:83], v[60:63], v[72:75]
	s_waitcnt lgkmcnt(2)
	v_pk_mul_f32 v[42:43], v[42:43], v[152:153]
	v_pk_mul_f32 v[40:41], v[40:41], v[150:151]
	v_add_u32_e32 v1, s74, v1
	v_mfma_f32_16x16x32_bf16 v[52:55], v[84:87], v[52:55], v[64:67]
	s_waitcnt lgkmcnt(0)
	v_mfma_f32_16x16x32_bf16 v[40:43], v[154:157], v[68:71], v[40:43]
	ds_read_b128 v[150:153], v137 offset:35008
	ds_read_b64_tr_b16 v[154:155], v138 offset:17504
	ds_read_b64_tr_b16 v[156:157], v138 offset:19808
	s_waitcnt lgkmcnt(2)
	v_pk_mul_f32 v[38:39], v[38:39], v[152:153]
	v_mfma_f32_16x16x32_bf16 v[56:59], v[84:87], v[56:59], v[60:63]
	v_mul_f32_e64 v36, v36, v150
	v_mul_f32_e64 v37, v37, v151
	s_nop 0
	v_cndmask_b32_e64 v60, v1, v0, s[4:5]
	v_cvt_pk_bf16_f32 v1, v54, v55
	v_add_u32_e32 v54, s73, v3
	v_ashrrev_i32_e32 v55, 31, v54
	v_lshlrev_b64 v[54:55], 11, v[54:55]
	v_cvt_pk_bf16_f32 v0, v52, v53
	v_lshl_add_u64 v[54:55], v[124:125], 0, v[54:55]
	v_mfma_f32_16x16x32_bf16 v[44:47], v[158:161], v[68:71], v[44:47]
	global_store_dwordx2 v[54:55], v[0:1], off offset:1024
	v_add_u32_e32 v0, s73, v60
	v_ashrrev_i32_e32 v1, 31, v0
	s_waitcnt lgkmcnt(0)
	v_mfma_f32_16x16x32_bf16 v[36:39], v[154:157], v[68:71], v[36:39]
	v_lshlrev_b64 v[0:1], 11, v[0:1]
	v_cvt_pk_bf16_f32 v52, v56, v57
	v_cvt_pk_bf16_f32 v53, v58, v59
	v_lshl_add_u64 v[0:1], v[124:125], 0, v[0:1]
	global_store_dwordx2 v[0:1], v[52:53], off offset:1024
	s_and_saveexec_b64 s[80:81], vcc
	s_cbranch_execz .LBB0_868
	v_cvt_f32_f16_e32 v0, v28
	v_cvt_f32_f16_sdwa v1, v28 dst_sel:DWORD dst_unused:UNUSED_PAD src0_sel:WORD_1
	v_cvt_f32_f16_e32 v3, v29
	v_cvt_f32_f16_sdwa v28, v29 dst_sel:DWORD dst_unused:UNUSED_PAD src0_sel:WORD_1
	v_add_f32_dpp v0, v0, v0 row_shr:1 row_mask:0xf bank_mask:0xf bound_ctrl:1
	v_add_f32_dpp v1, v1, v1 row_shr:1 row_mask:0xf bank_mask:0xf bound_ctrl:1
	v_mov_b32_e32 v53, v2
	v_add_f32_dpp v0, v0, v0 row_shr:2 row_mask:0xf bank_mask:0xf bound_ctrl:1
	v_add_f32_dpp v1, v1, v1 row_shr:2 row_mask:0xf bank_mask:0xf bound_ctrl:1
	v_cvt_f32_f16_e32 v29, v30
	v_add_f32_dpp v0, v0, v0 row_shr:4 row_mask:0xf bank_mask:0xf bound_ctrl:1
	v_add_f32_dpp v3, v3, v3 row_shr:1 row_mask:0xf bank_mask:0xf bound_ctrl:1
	v_add_f32_dpp v1, v1, v1 row_shr:4 row_mask:0xf bank_mask:0xf bound_ctrl:1
	v_add_f32_dpp v0, v0, v0 row_shr:8 row_mask:0xf bank_mask:0xf bound_ctrl:1
	v_add_f32_dpp v3, v3, v3 row_shr:2 row_mask:0xf bank_mask:0xf bound_ctrl:1
	v_add_f32_dpp v1, v1, v1 row_shr:8 row_mask:0xf bank_mask:0xf bound_ctrl:1
	v_mov_b32_dpp v53, v0 row_bcast:15 row_mask:0xa bank_mask:0xf
	v_add_f32_e32 v62, v0, v53
	v_mov_b32_e32 v0, v2
	v_cvt_f32_f16_sdwa v30, v30 dst_sel:DWORD dst_unused:UNUSED_PAD src0_sel:WORD_1
	v_add_f32_dpp v28, v28, v28 row_shr:1 row_mask:0xf bank_mask:0xf bound_ctrl:1
	v_add_f32_dpp v3, v3, v3 row_shr:4 row_mask:0xf bank_mask:0xf bound_ctrl:1
	v_mov_b32_dpp v0, v1 row_bcast:15 row_mask:0xa bank_mask:0xf
	v_add_f32_dpp v28, v28, v28 row_shr:2 row_mask:0xf bank_mask:0xf bound_ctrl:1
	v_add_f32_dpp v3, v3, v3 row_shr:8 row_mask:0xf bank_mask:0xf bound_ctrl:1
	v_add_f32_e32 v63, v1, v0
	v_mov_b32_e32 v0, v2
	v_cvt_f32_f16_e32 v52, v31
	v_add_f32_dpp v29, v29, v29 row_shr:1 row_mask:0xf bank_mask:0xf bound_ctrl:1
	v_add_f32_dpp v28, v28, v28 row_shr:4 row_mask:0xf bank_mask:0xf bound_ctrl:1
	v_mov_b32_dpp v0, v3 row_bcast:15 row_mask:0xa bank_mask:0xf
	v_add_f32_dpp v29, v29, v29 row_shr:2 row_mask:0xf bank_mask:0xf bound_ctrl:1
	v_add_f32_dpp v28, v28, v28 row_shr:8 row_mask:0xf bank_mask:0xf bound_ctrl:1
	v_add_f32_e32 v64, v3, v0
	v_mov_b32_e32 v0, v2
	v_add_f32_dpp v30, v30, v30 row_shr:1 row_mask:0xf bank_mask:0xf bound_ctrl:1
	v_add_f32_dpp v29, v29, v29 row_shr:4 row_mask:0xf bank_mask:0xf bound_ctrl:1
	v_mov_b32_dpp v0, v28 row_bcast:15 row_mask:0xa bank_mask:0xf
	v_add_f32_dpp v30, v30, v30 row_shr:2 row_mask:0xf bank_mask:0xf bound_ctrl:1
	v_add_f32_dpp v29, v29, v29 row_shr:8 row_mask:0xf bank_mask:0xf bound_ctrl:1
	v_add_f32_e32 v65, v28, v0
	v_mov_b32_e32 v0, v2
	v_add_f32_dpp v52, v52, v52 row_shr:1 row_mask:0xf bank_mask:0xf bound_ctrl:1
	v_add_f32_dpp v30, v30, v30 row_shr:4 row_mask:0xf bank_mask:0xf bound_ctrl:1
	v_mov_b32_dpp v0, v29 row_bcast:15 row_mask:0xa bank_mask:0xf
	ds_bpermute_b32 v1, v129, v62
	v_add_f32_dpp v52, v52, v52 row_shr:2 row_mask:0xf bank_mask:0xf bound_ctrl:1
	v_add_f32_dpp v30, v30, v30 row_shr:8 row_mask:0xf bank_mask:0xf bound_ctrl:1
	v_add_f32_e32 v3, v29, v0
	v_mov_b32_e32 v0, v2
	v_add_f32_dpp v52, v52, v52 row_shr:4 row_mask:0xf bank_mask:0xf bound_ctrl:1
	v_cvt_f32_f16_sdwa v31, v31 dst_sel:DWORD dst_unused:UNUSED_PAD src0_sel:WORD_1
	v_mov_b32_dpp v0, v30 row_bcast:15 row_mask:0xa bank_mask:0xf
	v_add_f32_dpp v52, v52, v52 row_shr:8 row_mask:0xf bank_mask:0xf bound_ctrl:1
	v_add_f32_e32 v66, v30, v0
	v_mov_b32_e32 v0, v2
	v_add_f32_dpp v31, v31, v31 row_shr:1 row_mask:0xf bank_mask:0xf bound_ctrl:1
	ds_bpermute_b32 v30, v129, v64
	v_mov_b32_dpp v0, v52 row_bcast:15 row_mask:0xa bank_mask:0xf
	v_add_f32_e32 v67, v52, v0
	s_waitcnt lgkmcnt(1)
	v_sub_f32_e32 v0, v62, v1
	ds_bpermute_b32 v1, v129, v63
	v_add_f32_dpp v31, v31, v31 row_shr:2 row_mask:0xf bank_mask:0xf bound_ctrl:1
	v_med3_f32 v0, v0, s69, v189
	v_mul_f32_e32 v0, 0x3fb8aa3b, v0
	v_add_f32_dpp v31, v31, v31 row_shr:4 row_mask:0xf bank_mask:0xf bound_ctrl:1
	v_exp_f32_e32 v28, v0
	v_mov_b32_e32 v0, v2
	v_add_f32_dpp v31, v31, v31 row_shr:8 row_mask:0xf bank_mask:0xf bound_ctrl:1
	s_waitcnt lgkmcnt(0)
	v_sub_f32_e32 v1, v63, v1
	ds_bpermute_b32 v56, v129, v67
	v_mov_b32_dpp v0, v31 row_bcast:15 row_mask:0xa bank_mask:0xf
	v_med3_f32 v1, v1, s69, v189
	v_add_f32_e32 v68, v31, v0
	v_mul_f32_e32 v1, 0x3fb8aa3b, v1
	v_exp_f32_e32 v29, v1
	ds_bpermute_b32 v1, v129, v65
	ds_bpermute_b32 v54, v129, v3
	ds_bpermute_b32 v55, v129, v66
	ds_bpermute_b32 v57, v129, v68
	s_waitcnt lgkmcnt(4)
	v_sub_f32_e32 v56, v67, v56
	v_med3_f32 v56, v56, s69, v189
	v_mul_f32_e32 v56, 0x3fb8aa3b, v56
	v_sub_f32_e32 v30, v64, v30
	s_waitcnt lgkmcnt(3)
	v_sub_f32_e32 v1, v65, v1
	s_waitcnt lgkmcnt(2)
	v_sub_f32_e32 v54, v3, v54
	s_waitcnt lgkmcnt(1)
	v_sub_f32_e32 v55, v66, v55
	v_exp_f32_e32 v58, v56
	s_waitcnt lgkmcnt(0)
	v_sub_f32_e32 v56, v68, v57
	v_med3_f32 v30, v30, s69, v189
	v_med3_f32 v1, v1, s69, v189
	v_med3_f32 v54, v54, s69, v189
	v_med3_f32 v55, v55, s69, v189
	v_med3_f32 v56, v56, s69, v189
	v_mul_f32_e32 v30, 0x3fb8aa3b, v30
	v_mul_f32_e32 v1, 0x3fb8aa3b, v1
	v_mul_f32_e32 v54, 0x3fb8aa3b, v54
	v_mul_f32_e32 v55, 0x3fb8aa3b, v55
	v_mul_f32_e32 v56, 0x3fb8aa3b, v56
	v_exp_f32_e32 v30, v30
	v_exp_f32_e32 v31, v1
	v_exp_f32_e32 v54, v54
	v_exp_f32_e32 v55, v55
	v_exp_f32_e32 v59, v56
	ds_bpermute_b32 v0, v130, v28
	ds_bpermute_b32 v1, v130, v29
	ds_bpermute_b32 v52, v130, v30
	ds_bpermute_b32 v53, v130, v31
	ds_bpermute_b32 v60, v130, v54
	ds_bpermute_b32 v61, v130, v55
	ds_bpermute_b32 v56, v130, v58
	ds_bpermute_b32 v57, v130, v59
	s_and_saveexec_b64 s[16:17], s[6:7]
	s_cbranch_execz .LBB0_867
	v_mul_f32_e32 v62, 0x3fb8aa3b, v62
	v_mul_f32_e32 v63, 0x3fb8aa3b, v63
	v_mul_f32_e32 v64, 0x3fb8aa3b, v64
	v_mul_f32_e32 v65, 0x3fb8aa3b, v65
	v_exp_f32_e32 v62, v62
	v_exp_f32_e32 v63, v63
	v_exp_f32_e32 v64, v64
	v_exp_f32_e32 v65, v65
	v_mul_f32_e32 v3, 0x3fb8aa3b, v3
	ds_write_b128 v139, v[62:65]
	v_exp_f32_e32 v62, v3
	v_mul_f32_e32 v3, 0x3fb8aa3b, v66
	v_exp_f32_e32 v63, v3
	v_mul_f32_e32 v3, 0x3fb8aa3b, v67
	v_exp_f32_e32 v64, v3
	v_mul_f32_e32 v3, 0x3fb8aa3b, v68
	v_exp_f32_e32 v65, v3
	ds_write_b128 v139, v[62:65] offset:16
	s_branch .LBB0_867

.LBB0_882:
	s_or_b64 exec, exec, s[56:57]
	s_min_i32 s16, s28, s35
	s_lshl_b32 s16, s16, 5
	v_or_b32_e32 v0, s16, v89
	v_xad_u32 v1, v0, -1, s74
	v_cndmask_b32_e64 v0, v1, v0, s[4:5]
	v_add_u32_e32 v1, s16, v90
	v_xad_u32 v3, v1, -1, s74
	v_add_u32_e32 v0, s73, v0
	v_cndmask_b32_e64 v3, v3, v1, s[4:5]
	v_ashrrev_i32_e32 v1, 31, v0
	ds_write_b128 v95, v[4:7] offset:61952
	v_mad_i64_i32 v[4:5], s[16:17], v0, s89, v[80:81]
	v_lshlrev_b64 v[0:1], 11, v[0:1]
	v_lshl_add_u64 v[0:1], v[82:83], 0, v[0:1]
	global_load_dwordx4 v[12:15], v[4:5], off
	global_load_dwordx4 v[20:23], v[0:1], off
	v_add_u32_e32 v0, s73, v3
	v_mad_i64_i32 v[0:1], s[16:17], v0, s89, v[84:85]
	global_load_dwordx4 v[4:7], v[0:1], off
	v_add_u32_e32 v0, 0x8800, v97
	s_waitcnt lgkmcnt(0)
	s_barrier
	ds_read_b64_tr_b16 v[60:61], v102
	ds_read_b64_tr_b16 v[62:63], v102 offset:4352
	ds_read_b64 v[56:57], v0 offset:1024
	ds_read_b64 v[58:59], v0 offset:1056
	ds_read_b64 v[44:45], v0 offset:1088
	ds_read_b64 v[46:47], v0 offset:1120
	v_add_u32_e32 v0, 0x9000, v97
	ds_read_b64 v[52:53], v0 offset:1280
	ds_read_b64 v[54:55], v0 offset:1312
	ds_read_b64 v[48:49], v0 offset:1344
	ds_read_b64 v[50:51], v0 offset:1376
	v_add_u32_e32 v0, 0xa800, v98
	v_add_u32_e32 v1, 0xb000, v98
	ds_read_b64 v[64:65], v0 offset:1536
	ds_read_b64 v[66:67], v0 offset:1568
	ds_read_b64 v[68:69], v1 offset:1792
	ds_read_b64 v[70:71], v1 offset:1824
	ds_read_b64 v[76:77], v0 offset:1600
	ds_read_b64 v[78:79], v0 offset:1632
	ds_read_b64 v[112:113], v1 offset:1856
	ds_read_b64 v[114:115], v1 offset:1888
	s_waitcnt lgkmcnt(6)
	v_mfma_f32_16x16x32_bf16 v[72:75], v[64:67], v[56:59], 0
	v_mov_b32_e32 v0, s93
	s_add_i32 s28, s28, 2
	v_subrev_u32_e32 v111, 64, v111
	s_waitcnt lgkmcnt(4)
	v_mfma_f32_16x16x32_bf16 v[68:71], v[68:71], v[52:55], 0
	s_cmp_lt_u32 s58, s3
	s_waitcnt lgkmcnt(2)
	v_mfma_f32_16x16x32_bf16 v[72:75], v[76:79], v[44:47], v[72:75]
	s_waitcnt lgkmcnt(0)
	v_mfma_f32_16x16x32_bf16 v[68:71], v[112:115], v[48:51], v[68:71]
	v_mov_b32_e32 v112, s93
	s_nop 4
	v_cndmask_b32_e64 v0, v72, v0, s[8:9]
	v_cndmask_b32_e64 v0, v0, v72, s[10:11]
	v_mfma_f32_16x16x32_bf16 v[64:67], v[64:67], v[52:55], 0
	v_cndmask_b32_e64 v3, v74, 0, s[12:13]
	v_cndmask_b32_e64 v1, v68, v112, s[8:9]
	v_cndmask_b32_e64 v68, v1, v68, s[10:11]
	v_cndmask_b32_e64 v1, 0, v73, s[10:11]
	v_cndmask_b32_e64 v72, v75, 0, s[14:15]
	v_mfma_f32_16x16x32_bf16 v[64:67], v[76:79], v[48:51], v[64:67]
	v_cvt_pk_bf16_f32 v0, v0, v1
	v_cvt_pk_bf16_f32 v1, v3, v72
	ds_read_b128 v[72:75], v103
	ds_read_b128 v[76:79], v104
	v_cndmask_b32_e64 v69, 0, v69, s[10:11]
	v_cndmask_b32_e64 v70, v70, 0, s[12:13]
	v_cndmask_b32_e64 v71, v71, 0, s[14:15]
	v_mov_b32_e32 v3, v2
	v_cvt_pk_bf16_f32 v64, v64, v65
	v_cvt_pk_bf16_f32 v65, v66, v67
	v_cvt_pk_bf16_f32 v66, v68, v69
	v_cvt_pk_bf16_f32 v67, v70, v71
	v_mfma_f32_16x16x32_bf16 v[68:71], v[60:63], v[0:3], 0
	s_waitcnt lgkmcnt(1)
	v_pk_mul_f32 v[0:1], v[42:43], v[74:75]
	s_waitcnt lgkmcnt(0)
	v_pk_mul_f32 v[78:79], v[38:39], v[78:79]
	v_pk_mul_f32 v[74:75], v[36:37], v[76:77]
	v_pk_mul_f32 v[72:73], v[40:41], v[72:73]
	v_cvt_pk_bf16_f32 v74, v74, v75
	v_cvt_pk_bf16_f32 v75, v78, v79
	ds_read_b128 v[76:79], v105
	ds_read_b128 v[112:115], v106
	v_cvt_pk_bf16_f32 v72, v72, v73
	v_cvt_pk_bf16_f32 v73, v0, v1
	v_mfma_f32_16x16x32_bf16 v[64:67], v[60:63], v[64:67], 0
	s_waitcnt lgkmcnt(1)
	v_pk_mul_f32 v[0:1], v[30:31], v[78:79]
	s_waitcnt lgkmcnt(0)
	v_pk_mul_f32 v[114:115], v[34:35], v[114:115]
	v_pk_mul_f32 v[78:79], v[32:33], v[112:113]
	v_pk_mul_f32 v[76:77], v[28:29], v[76:77]
	v_cvt_pk_bf16_f32 v78, v78, v79
	v_cvt_pk_bf16_f32 v79, v114, v115
	ds_read_b128 v[112:115], v107
	ds_read_b64_tr_b16 v[118:119], v100 offset:55552
	ds_read_b64_tr_b16 v[116:117], v100 offset:53248
	ds_read_b64_tr_b16 v[120:121], v100 offset:53280
	v_cvt_pk_bf16_f32 v76, v76, v77
	s_waitcnt lgkmcnt(3)
	v_pk_mul_f32 v[42:43], v[42:43], v[114:115]
	v_pk_mul_f32 v[40:41], v[40:41], v[112:113]
	ds_read_b128 v[112:115], v108
	ds_read_b64_tr_b16 v[122:123], v100 offset:55584
	v_cvt_pk_bf16_f32 v77, v0, v1
	v_mfma_f32_16x16x32_bf16 v[56:59], v[72:75], v[56:59], v[68:71]
	v_xor_b32_e32 v3, 0xffffffdf, v88
	s_waitcnt lgkmcnt(1)
	v_pk_mul_f32 v[38:39], v[38:39], v[114:115]
	v_pk_mul_f32 v[36:37], v[36:37], v[112:113]
	v_mfma_f32_16x16x32_bf16 v[40:43], v[116:119], v[60:63], v[40:43]
	ds_read_b128 v[112:115], v109
	ds_read_b64_tr_b16 v[116:117], v100 offset:53312
	ds_read_b64_tr_b16 v[118:119], v100 offset:55616
	v_add_u32_e32 v0, 32, v88
	v_add_u32_e32 v3, s74, v3
	v_mfma_f32_16x16x32_bf16 v[52:55], v[72:75], v[52:55], v[64:67]
	s_waitcnt lgkmcnt(2)
	v_pk_mul_f32 v[30:31], v[30:31], v[114:115]
	v_pk_mul_f32 v[28:29], v[28:29], v[112:113]
	v_cndmask_b32_e64 v3, v3, v0, s[4:5]
	v_mfma_f32_16x16x32_bf16 v[44:47], v[76:79], v[44:47], v[56:59]
	v_xor_b32_e32 v0, 0xffffffcf, v88
	v_add_u32_e32 v1, 48, v88
	v_add_u32_e32 v0, s74, v0
	s_waitcnt lgkmcnt(0)
	v_mfma_f32_16x16x32_bf16 v[28:31], v[116:119], v[60:63], v[28:31]
	ds_read_b128 v[112:115], v110
	ds_read_b64_tr_b16 v[116:117], v100 offset:53344
	ds_read_b64_tr_b16 v[118:119], v100 offset:55648
	v_add_u32_e32 v88, 64, v88
	s_waitcnt lgkmcnt(2)
	v_pk_mul_f32 v[34:35], v[34:35], v[114:115]
	v_mfma_f32_16x16x32_bf16 v[48:51], v[76:79], v[48:51], v[52:55]
	v_mul_f32_e64 v32, v32, v112
	v_mul_f32_e64 v33, v33, v113
	s_nop 0
	v_cndmask_b32_e64 v52, v0, v1, s[4:5]
	v_cvt_pk_bf16_f32 v1, v46, v47
	v_add_u32_e32 v46, s73, v3
	v_ashrrev_i32_e32 v47, 31, v46
	v_lshlrev_b64 v[46:47], 11, v[46:47]
	v_cvt_pk_bf16_f32 v0, v44, v45
	v_lshl_add_u64 v[46:47], v[86:87], 0, v[46:47]
	v_mfma_f32_16x16x32_bf16 v[36:39], v[120:123], v[60:63], v[36:39]
	global_store_dwordx2 v[46:47], v[0:1], off
	v_add_u32_e32 v0, s73, v52
	v_ashrrev_i32_e32 v1, 31, v0
	s_waitcnt lgkmcnt(0)
	v_mfma_f32_16x16x32_bf16 v[32:35], v[116:119], v[60:63], v[32:35]
	v_lshlrev_b64 v[0:1], 11, v[0:1]
	v_cvt_pk_bf16_f32 v44, v48, v49
	v_cvt_pk_bf16_f32 v45, v50, v51
	v_lshl_add_u64 v[0:1], v[86:87], 0, v[0:1]
	global_store_dwordx2 v[0:1], v[44:45], off
	s_cbranch_scc0 .LBB0_815

.LBB0_887:
	s_or_b64 exec, exec, s[56:57]
	s_add_i32 s58, s28, -1
	s_min_i32 s16, s58, s35
	s_lshl_b32 s16, s16, 5
	v_or_b32_e32 v0, s16, v89
	v_xad_u32 v1, v0, -1, s74
	v_cndmask_b32_e64 v0, v1, v0, s[4:5]
	v_add_u32_e32 v1, s16, v90
	v_xad_u32 v3, v1, -1, s74
	v_add_u32_e32 v0, s73, v0
	v_cndmask_b32_e64 v3, v3, v1, s[4:5]
	v_ashrrev_i32_e32 v1, 31, v0
	s_waitcnt vmcnt(2)
	ds_write_b128 v95, v[8:11] offset:26112
	v_mad_i64_i32 v[8:9], s[16:17], v0, s89, v[80:81]
	v_lshlrev_b64 v[0:1], 11, v[0:1]
	v_lshl_add_u64 v[0:1], v[82:83], 0, v[0:1]
	global_load_dwordx4 v[16:19], v[8:9], off
	global_load_dwordx4 v[24:27], v[0:1], off
	v_add_u32_e32 v0, s73, v3
	v_mad_i64_i32 v[0:1], s[16:17], v0, s89, v[84:85]
	global_load_dwordx4 v[8:11], v[0:1], off
	v_add_u32_e32 v0, 0x800, v97
	s_waitcnt lgkmcnt(0)
	s_barrier
	ds_read_b64_tr_b16 v[60:61], v96 offset:26112
	ds_read_b64_tr_b16 v[62:63], v96 offset:30464
	ds_read_b64 v[56:57], v97
	ds_read_b64 v[58:59], v97 offset:32
	ds_read_b64 v[44:45], v97 offset:64
	ds_read_b64 v[46:47], v97 offset:96
	ds_read_b64 v[52:53], v0 offset:256
	ds_read_b64 v[54:55], v0 offset:288
	ds_read_b64 v[48:49], v0 offset:320
	ds_read_b64 v[50:51], v0 offset:352
	v_add_u32_e32 v0, 0x2000, v98
	v_add_u32_e32 v1, 0x2800, v98
	ds_read_b64 v[64:65], v0 offset:512
	ds_read_b64 v[66:67], v0 offset:544
	ds_read_b64 v[68:69], v1 offset:768
	ds_read_b64 v[70:71], v1 offset:800
	ds_read_b64 v[76:77], v0 offset:576
	ds_read_b64 v[78:79], v0 offset:608
	ds_read_b64 v[112:113], v1 offset:832
	ds_read_b64 v[114:115], v1 offset:864
	s_waitcnt lgkmcnt(6)
	v_mfma_f32_16x16x32_bf16 v[72:75], v[64:67], v[56:59], 0
	v_mov_b32_e32 v0, s93
	s_waitcnt lgkmcnt(4)
	v_mfma_f32_16x16x32_bf16 v[68:71], v[68:71], v[52:55], 0
	s_waitcnt lgkmcnt(2)
	v_mfma_f32_16x16x32_bf16 v[72:75], v[76:79], v[44:47], v[72:75]
	s_waitcnt lgkmcnt(0)
	v_mfma_f32_16x16x32_bf16 v[68:71], v[112:115], v[48:51], v[68:71]
	v_mov_b32_e32 v112, s93
	s_nop 4
	v_cndmask_b32_e64 v0, v72, v0, s[8:9]
	v_cndmask_b32_e64 v0, v0, v72, s[10:11]
	v_mfma_f32_16x16x32_bf16 v[64:67], v[64:67], v[52:55], 0
	v_cndmask_b32_e64 v3, v74, 0, s[12:13]
	v_cndmask_b32_e64 v1, v68, v112, s[8:9]
	v_cndmask_b32_e64 v68, v1, v68, s[10:11]
	v_cndmask_b32_e64 v1, 0, v73, s[10:11]
	v_cndmask_b32_e64 v72, v75, 0, s[14:15]
	v_mfma_f32_16x16x32_bf16 v[64:67], v[76:79], v[48:51], v[64:67]
	v_cvt_pk_bf16_f32 v0, v0, v1
	v_cvt_pk_bf16_f32 v1, v3, v72
	ds_read_b128 v[72:75], v99 offset:35328
	ds_read_b128 v[76:79], v99 offset:35392
	v_cndmask_b32_e64 v69, 0, v69, s[10:11]
	v_cndmask_b32_e64 v70, v70, 0, s[12:13]
	v_cndmask_b32_e64 v71, v71, 0, s[14:15]
	v_mov_b32_e32 v3, v2
	v_cvt_pk_bf16_f32 v64, v64, v65
	v_cvt_pk_bf16_f32 v65, v66, v67
	v_cvt_pk_bf16_f32 v66, v68, v69
	v_cvt_pk_bf16_f32 v67, v70, v71
	v_mfma_f32_16x16x32_bf16 v[68:71], v[60:63], v[0:3], 0
	s_waitcnt lgkmcnt(1)
	v_pk_mul_f32 v[0:1], v[42:43], v[74:75]
	s_waitcnt lgkmcnt(0)
	v_pk_mul_f32 v[78:79], v[38:39], v[78:79]
	v_pk_mul_f32 v[74:75], v[36:37], v[76:77]
	v_pk_mul_f32 v[72:73], v[40:41], v[72:73]
	v_cvt_pk_bf16_f32 v74, v74, v75
	v_cvt_pk_bf16_f32 v75, v78, v79
	ds_read_b128 v[76:79], v99 offset:35456
	ds_read_b128 v[112:115], v99 offset:35520
	v_cvt_pk_bf16_f32 v72, v72, v73
	v_cvt_pk_bf16_f32 v73, v0, v1
	v_mfma_f32_16x16x32_bf16 v[64:67], v[60:63], v[64:67], 0
	s_waitcnt lgkmcnt(1)
	v_pk_mul_f32 v[0:1], v[30:31], v[78:79]
	s_waitcnt lgkmcnt(0)
	v_pk_mul_f32 v[114:115], v[34:35], v[114:115]
	v_pk_mul_f32 v[78:79], v[32:33], v[112:113]
	v_pk_mul_f32 v[76:77], v[28:29], v[76:77]
	v_cvt_pk_bf16_f32 v78, v78, v79
	v_cvt_pk_bf16_f32 v79, v114, v115
	ds_read_b128 v[112:115], v99 offset:34816
	ds_read_b64_tr_b16 v[118:119], v100 offset:19712
	ds_read_b64_tr_b16 v[116:117], v100 offset:17408
	ds_read_b64_tr_b16 v[120:121], v100 offset:17440
	v_cvt_pk_bf16_f32 v76, v76, v77
	s_waitcnt lgkmcnt(3)
	v_pk_mul_f32 v[42:43], v[42:43], v[114:115]
	v_pk_mul_f32 v[40:41], v[40:41], v[112:113]
	ds_read_b128 v[112:115], v99 offset:34880
	ds_read_b64_tr_b16 v[122:123], v100 offset:19744
	v_cvt_pk_bf16_f32 v77, v0, v1
	v_mfma_f32_16x16x32_bf16 v[56:59], v[72:75], v[56:59], v[68:71]
	v_xor_b32_e32 v1, 0xffffffef, v88
	s_waitcnt lgkmcnt(1)
	v_pk_mul_f32 v[38:39], v[38:39], v[114:115]
	v_pk_mul_f32 v[36:37], v[36:37], v[112:113]
	v_mfma_f32_16x16x32_bf16 v[40:43], v[116:119], v[60:63], v[40:43]
	ds_read_b128 v[112:115], v99 offset:34944
	ds_read_b64_tr_b16 v[116:117], v100 offset:17472
	ds_read_b64_tr_b16 v[118:119], v100 offset:19776
	v_add_u32_e32 v0, 16, v88
	v_cndmask_b32_e64 v3, v111, v88, s[4:5]
	v_mfma_f32_16x16x32_bf16 v[52:55], v[72:75], v[52:55], v[64:67]
	s_waitcnt lgkmcnt(2)
	v_pk_mul_f32 v[30:31], v[30:31], v[114:115]
	v_pk_mul_f32 v[28:29], v[28:29], v[112:113]
	v_add_u32_e32 v1, s74, v1
	v_mfma_f32_16x16x32_bf16 v[44:47], v[76:79], v[44:47], v[56:59]
	s_waitcnt lgkmcnt(0)
	v_mfma_f32_16x16x32_bf16 v[28:31], v[116:119], v[60:63], v[28:31]
	ds_read_b128 v[112:115], v99 offset:35008
	ds_read_b64_tr_b16 v[116:117], v100 offset:17504
	ds_read_b64_tr_b16 v[118:119], v100 offset:19808
	s_waitcnt lgkmcnt(2)
	v_pk_mul_f32 v[34:35], v[34:35], v[114:115]
	v_mfma_f32_16x16x32_bf16 v[48:51], v[76:79], v[48:51], v[52:55]
	v_mul_f32_e64 v32, v32, v112
	v_mul_f32_e64 v33, v33, v113
	s_nop 0
	v_cndmask_b32_e64 v52, v1, v0, s[4:5]
	v_cvt_pk_bf16_f32 v1, v46, v47
	v_add_u32_e32 v46, s73, v3
	v_ashrrev_i32_e32 v47, 31, v46
	v_lshlrev_b64 v[46:47], 11, v[46:47]
	v_cvt_pk_bf16_f32 v0, v44, v45
	v_lshl_add_u64 v[46:47], v[86:87], 0, v[46:47]
	v_mfma_f32_16x16x32_bf16 v[36:39], v[120:123], v[60:63], v[36:39]
	global_store_dwordx2 v[46:47], v[0:1], off
	v_add_u32_e32 v0, s73, v52
	v_ashrrev_i32_e32 v1, 31, v0
	s_waitcnt lgkmcnt(0)
	v_mfma_f32_16x16x32_bf16 v[32:35], v[116:119], v[60:63], v[32:35]
	v_lshlrev_b64 v[0:1], 11, v[0:1]
	v_cvt_pk_bf16_f32 v44, v48, v49
	v_cvt_pk_bf16_f32 v45, v50, v51
	v_lshl_add_u64 v[0:1], v[86:87], 0, v[0:1]
	global_store_dwordx2 v[0:1], v[44:45], off
	s_and_saveexec_b64 s[56:57], vcc
	s_cbranch_execz .LBB0_882
	v_cvt_f32_f16_e32 v60, v20
	v_cvt_f32_f16_sdwa v59, v20 dst_sel:DWORD dst_unused:UNUSED_PAD src0_sel:WORD_1
	v_cvt_f32_f16_e32 v58, v21
	v_cvt_f32_f16_sdwa v57, v21 dst_sel:DWORD dst_unused:UNUSED_PAD src0_sel:WORD_1
	v_add_f32_dpp v0, v60, v60 row_shr:1 row_mask:0xf bank_mask:0xf bound_ctrl:1
	v_add_f32_dpp v1, v59, v59 row_shr:1 row_mask:0xf bank_mask:0xf bound_ctrl:1
	v_mov_b32_e32 v46, v2
	v_add_f32_dpp v0, v0, v0 row_shr:2 row_mask:0xf bank_mask:0xf bound_ctrl:1
	v_add_f32_dpp v1, v1, v1 row_shr:2 row_mask:0xf bank_mask:0xf bound_ctrl:1
	v_cvt_f32_f16_e32 v56, v22
	v_add_f32_dpp v0, v0, v0 row_shr:4 row_mask:0xf bank_mask:0xf bound_ctrl:1
	v_add_f32_dpp v20, v58, v58 row_shr:1 row_mask:0xf bank_mask:0xf bound_ctrl:1
	v_add_f32_dpp v1, v1, v1 row_shr:4 row_mask:0xf bank_mask:0xf bound_ctrl:1
	v_add_f32_dpp v0, v0, v0 row_shr:8 row_mask:0xf bank_mask:0xf bound_ctrl:1
	v_add_f32_dpp v20, v20, v20 row_shr:2 row_mask:0xf bank_mask:0xf bound_ctrl:1
	v_add_f32_dpp v1, v1, v1 row_shr:8 row_mask:0xf bank_mask:0xf bound_ctrl:1
	v_mov_b32_dpp v46, v0 row_bcast:15 row_mask:0xa bank_mask:0xf
	v_add_f32_e32 v62, v0, v46
	v_mov_b32_e32 v0, v2
	v_cvt_f32_f16_sdwa v55, v22 dst_sel:DWORD dst_unused:UNUSED_PAD src0_sel:WORD_1
	v_add_f32_dpp v21, v57, v57 row_shr:1 row_mask:0xf bank_mask:0xf bound_ctrl:1
	v_add_f32_dpp v20, v20, v20 row_shr:4 row_mask:0xf bank_mask:0xf bound_ctrl:1
	v_mov_b32_dpp v0, v1 row_bcast:15 row_mask:0xa bank_mask:0xf
	v_add_f32_dpp v21, v21, v21 row_shr:2 row_mask:0xf bank_mask:0xf bound_ctrl:1
	v_add_f32_dpp v20, v20, v20 row_shr:8 row_mask:0xf bank_mask:0xf bound_ctrl:1
	v_add_f32_e32 v63, v1, v0
	v_mov_b32_e32 v0, v2
	v_cvt_f32_f16_e32 v54, v23
	v_add_f32_dpp v22, v56, v56 row_shr:1 row_mask:0xf bank_mask:0xf bound_ctrl:1
	v_add_f32_dpp v21, v21, v21 row_shr:4 row_mask:0xf bank_mask:0xf bound_ctrl:1
	v_mov_b32_dpp v0, v20 row_bcast:15 row_mask:0xa bank_mask:0xf
	v_add_f32_dpp v22, v22, v22 row_shr:2 row_mask:0xf bank_mask:0xf bound_ctrl:1
	v_add_f32_dpp v21, v21, v21 row_shr:8 row_mask:0xf bank_mask:0xf bound_ctrl:1
	v_add_f32_e32 v64, v20, v0
	v_mov_b32_e32 v0, v2
	v_cvt_f32_f16_sdwa v3, v23 dst_sel:DWORD dst_unused:UNUSED_PAD src0_sel:WORD_1
	v_add_f32_dpp v23, v55, v55 row_shr:1 row_mask:0xf bank_mask:0xf bound_ctrl:1
	v_add_f32_dpp v22, v22, v22 row_shr:4 row_mask:0xf bank_mask:0xf bound_ctrl:1
	v_mov_b32_dpp v0, v21 row_bcast:15 row_mask:0xa bank_mask:0xf
	v_add_f32_dpp v23, v23, v23 row_shr:2 row_mask:0xf bank_mask:0xf bound_ctrl:1
	v_add_f32_dpp v22, v22, v22 row_shr:8 row_mask:0xf bank_mask:0xf bound_ctrl:1
	v_add_f32_e32 v65, v21, v0
	v_mov_b32_e32 v0, v2
	v_add_f32_dpp v44, v54, v54 row_shr:1 row_mask:0xf bank_mask:0xf bound_ctrl:1
	v_add_f32_dpp v23, v23, v23 row_shr:4 row_mask:0xf bank_mask:0xf bound_ctrl:1
	v_mov_b32_dpp v0, v22 row_bcast:15 row_mask:0xa bank_mask:0xf
	ds_bpermute_b32 v1, v91, v62
	v_add_f32_dpp v44, v44, v44 row_shr:2 row_mask:0xf bank_mask:0xf bound_ctrl:1
	v_add_f32_dpp v23, v23, v23 row_shr:8 row_mask:0xf bank_mask:0xf bound_ctrl:1
	v_add_f32_e32 v61, v22, v0
	v_mov_b32_e32 v0, v2
	v_add_f32_dpp v44, v44, v44 row_shr:4 row_mask:0xf bank_mask:0xf bound_ctrl:1
	v_add_f32_dpp v45, v3, v3 row_shr:1 row_mask:0xf bank_mask:0xf bound_ctrl:1
	v_mov_b32_dpp v0, v23 row_bcast:15 row_mask:0xa bank_mask:0xf
	v_add_f32_dpp v44, v44, v44 row_shr:8 row_mask:0xf bank_mask:0xf bound_ctrl:1
	v_add_f32_e32 v66, v23, v0
	v_mov_b32_e32 v0, v2
	v_add_f32_dpp v45, v45, v45 row_shr:2 row_mask:0xf bank_mask:0xf bound_ctrl:1
	ds_bpermute_b32 v22, v91, v64
	v_mov_b32_dpp v0, v44 row_bcast:15 row_mask:0xa bank_mask:0xf
	v_add_f32_e32 v67, v44, v0
	s_waitcnt lgkmcnt(1)
	v_sub_f32_e32 v0, v62, v1
	ds_bpermute_b32 v1, v91, v63
	v_med3_f32 v0, v0, s69, v189
	v_add_f32_dpp v45, v45, v45 row_shr:4 row_mask:0xf bank_mask:0xf bound_ctrl:1
	v_mul_f32_e32 v0, 0x3fb8aa3b, v0
	v_exp_f32_e32 v20, v0
	v_add_f32_dpp v45, v45, v45 row_shr:8 row_mask:0xf bank_mask:0xf bound_ctrl:1
	v_mov_b32_e32 v0, v2
	s_waitcnt lgkmcnt(0)
	v_sub_f32_e32 v1, v63, v1
	v_med3_f32 v1, v1, s69, v189
	v_mov_b32_dpp v0, v45 row_bcast:15 row_mask:0xa bank_mask:0xf
	v_add_f32_e32 v68, v45, v0
	v_mul_f32_e32 v1, 0x3fb8aa3b, v1
	v_exp_f32_e32 v21, v1
	ds_bpermute_b32 v1, v91, v65
	ds_bpermute_b32 v46, v91, v61
	ds_bpermute_b32 v47, v91, v66
	ds_bpermute_b32 v48, v91, v67
	ds_bpermute_b32 v49, v91, v68
	v_sub_f32_e32 v22, v64, v22
	s_waitcnt lgkmcnt(4)
	v_sub_f32_e32 v1, v65, v1
	s_waitcnt lgkmcnt(3)
	v_sub_f32_e32 v46, v61, v46
	s_waitcnt lgkmcnt(2)
	v_sub_f32_e32 v47, v66, v47
	s_waitcnt lgkmcnt(1)
	v_sub_f32_e32 v48, v67, v48
	s_waitcnt lgkmcnt(0)
	v_sub_f32_e32 v49, v68, v49
	v_med3_f32 v22, v22, s69, v189
	v_med3_f32 v1, v1, s69, v189
	v_med3_f32 v46, v46, s69, v189
	v_med3_f32 v47, v47, s69, v189
	v_med3_f32 v48, v48, s69, v189
	v_med3_f32 v49, v49, s69, v189
	v_mul_f32_e32 v22, 0x3fb8aa3b, v22
	v_mul_f32_e32 v1, 0x3fb8aa3b, v1
	v_mul_f32_e32 v46, 0x3fb8aa3b, v46
	v_mul_f32_e32 v47, 0x3fb8aa3b, v47
	v_mul_f32_e32 v48, 0x3fb8aa3b, v48
	v_mul_f32_e32 v49, 0x3fb8aa3b, v49
	v_exp_f32_e32 v44, v22
	v_exp_f32_e32 v45, v1
	v_exp_f32_e32 v46, v46
	v_exp_f32_e32 v47, v47
	v_exp_f32_e32 v48, v48
	v_exp_f32_e32 v49, v49
	ds_bpermute_b32 v0, v92, v20
	ds_bpermute_b32 v1, v92, v21
	ds_bpermute_b32 v22, v92, v44
	ds_bpermute_b32 v23, v92, v45
	ds_bpermute_b32 v52, v92, v46
	ds_bpermute_b32 v53, v92, v47
	ds_bpermute_b32 v50, v92, v48
	ds_bpermute_b32 v51, v92, v49
	s_and_saveexec_b64 s[16:17], s[6:7]
	s_cbranch_execz .LBB0_881
	v_mul_f32_e32 v62, 0x3fb8aa3b, v62
	v_mul_f32_e32 v63, 0x3fb8aa3b, v63
	v_mul_f32_e32 v64, 0x3fb8aa3b, v64
	v_mul_f32_e32 v65, 0x3fb8aa3b, v65
	v_exp_f32_e32 v62, v62
	v_exp_f32_e32 v63, v63
	v_exp_f32_e32 v64, v64
	v_exp_f32_e32 v65, v65
	v_mul_f32_e32 v61, 0x3fb8aa3b, v61
	ds_write_b128 v101, v[62:65]
	v_exp_f32_e32 v62, v61
	v_mul_f32_e32 v61, 0x3fb8aa3b, v66
	v_exp_f32_e32 v63, v61
	v_mul_f32_e32 v61, 0x3fb8aa3b, v67
	v_exp_f32_e32 v64, v61
	v_mul_f32_e32 v61, 0x3fb8aa3b, v68
	v_exp_f32_e32 v65, v61
	ds_write_b128 v101, v[62:65] offset:16
	s_branch .LBB0_881
